# v102: v101 + s_setprio raise moved in front of the barrier that opens each MFMA segment and the lower behind the barrier that closes it (no SALU between barrier and MFMAs)
# speedup vs baseline: 1.0089x; 1.0026x over previous
; #define PG8_STAGE(bufoff, gbase, voff) do { _Pragma("unroll") for (int _i = 0; _i < 2; ++_i) \
;         __builtin_amdgcn_global_load_lds((const unsigned*)((const char*)(gbase) + (voff)[_i]), (PG8_LAS unsigned*)(lds + (bufoff) + ldsw + _i * 8192), 16, 0, 0); } while (0)
; #define PG8_LDA(dst, b, h) do { _Pragma("unroll") for (int m = 0; m < 4; ++m) _Pragma("unroll") for (int k = 0; k < 2; ++k) dst[m][k] = *(const PG8_LAS bf16x8*)(lds + PG8_SA(b, h) + aoff + m * 2048 + k * 1024); } while (0)
; #define PG8_LDB(dst, b, h) do { _Pragma("unroll") for (int n = 0; n < 2; ++n) _Pragma("unroll") for (int k = 0; k < 2; ++k) dst[n][k] = *(const PG8_LAS bf16x8*)(lds + PG8_SB(b, h) + boff + n * 2048 + k * 1024); } while (0)
; #define PG8_WAIT_V(n) asm volatile("s_waitcnt vmcnt(" #n ")" ::: "memory")
; #define PG8_WAIT_L(n) asm volatile("s_waitcnt lgkmcnt(" #n ")" ::: "memory")
; #define PG8_BAR __builtin_amdgcn_s_barrier()
; #define PG8_SCHED __builtin_amdgcn_sched_barrier(0)
; template <class Epi, class Sched, bool ALIGN_EPI, int LMASK = -1, int LMASKB = LMASK>
; __device__ __forceinline__ void gemm_phase(PG8_LAS unsigned char* lds, const Gemm g, const Sched& S, const Epi& E) {
;     ...
;         const bool has_next = S.next(ui + 1, nxt);
;         const char* nA = has_next ? (const char*)g.A + (size_t)(nxt.pm & LMASK) * tstepA : cA; const char* nB = has_next ? (const char*)g.Bt + (size_t)nxt.pm * g.b_pm_stride + (size_t)(nxt.pn & LMASKB) * tstepB : cB;
;         for (int t = 0; t < nt; t += 2) {
;             const bool last = (t == nt - 2);
;             const char* a1 = cA + (size_t)(t + 1) * kstepA;
;             const char* a2 = last ? nA : cA + (size_t)(t + 2) * kstepA; const char* b2 = last ? nB : cB + (size_t)(t + 2) * kstepB;
;             const char* a3 = a2 + kstepA; const char* b3 = b2 + kstepB;
;             PG8_LDB(B0, 0, 0); PG8_LDB(B1, 0, 1); PG8_SCHED; PG8_LDA(At, 0, 0); PG8_STAGE(PG8_SA(1, 1), a1 + hstepA, voffA);
;             PG8_WAIT_V(8); PG8_WAIT_L(0); PG8_BAR; PG8_MMA(0, 0, At, B0); PG8_MMA(0, 1, At, B1); PG8_BAR; PG8_SCHED;
;             PG8_LDA(At, 0, 1); PG8_STAGE(PG8_SB(0, 0), b2, voffB); PG8_STAGE(PG8_SB(0, 1), b2 + hstepB, voffB); PG8_STAGE(PG8_SA(0, 0), a2, voffA);
;             PG8_WAIT_V(8); PG8_WAIT_L(0); PG8_BAR; PG8_MMA(1, 0, At, B0); PG8_MMA(1, 1, At, B1); PG8_BAR; PG8_SCHED;
.LBB0_206:
	s_ashr_i32 s17, s16, 31
	s_lshl_b64 s[2:3], s[16:17], 17
	s_add_u32 s20, s1, s2
	s_addc_u32 s21, s33, s3
	s_and_b64 s[2:3], s[4:5], exec
	s_cselect_b32 s29, s21, s23
	s_cselect_b32 s28, s20, s22
	s_lshl_b64 s[2:3], s[16:17], 21
	s_add_u32 s17, s36, s2
	ds_read_b128 v[2:5], v142
	ds_read_b128 v[6:9], v142 offset:1024
	ds_read_b128 v[10:13], v142 offset:2048
	ds_read_b128 v[14:17], v142 offset:3072
	ds_read_b128 v[18:21], v143
	ds_read_b128 v[22:25], v143 offset:1024
	ds_read_b128 v[26:29], v143 offset:2048
	ds_read_b128 v[30:33], v143 offset:3072
	s_addc_u32 s26, s37, s3
	s_ashr_i32 s15, s14, 31
	s_lshl_b64 s[2:3], s[14:15], 17
	s_add_u32 s2, s17, s2
	s_addc_u32 s3, s26, s3
	s_and_b64 s[26:27], s[4:5], exec
	s_cselect_b32 s27, s3, s25
	s_cselect_b32 s26, s2, s24
	s_add_u32 s34, s22, 0x1000
	s_addc_u32 s35, s23, 0
	s_add_u32 s54, s24, 0x1000
	s_addc_u32 s55, s25, 0
	s_add_u32 s30, s22, 0x1800
	s_addc_u32 s31, s23, 0
	s_add_u32 s56, s22, 0x10800
	s_addc_u32 s57, s23, 0
	s_mov_b32 m0, s50
	v_lshl_add_u64 v[66:67], s[56:57], 0, v[130:131]
	ds_read_b128 v[34:37], v144
	ds_read_b128 v[38:41], v144 offset:1024
	ds_read_b128 v[42:45], v144 offset:2048
	ds_read_b128 v[46:49], v144 offset:3072
	ds_read_b128 v[50:53], v144 offset:4096
	ds_read_b128 v[54:57], v144 offset:5120
	ds_read_b128 v[58:61], v144 offset:6144
	ds_read_b128 v[62:65], v144 offset:7168
	global_load_lds_dwordx4 v[66:67], off
	v_lshl_add_u64 v[66:67], s[56:57], 0, v[132:133]
	s_mov_b32 m0, s51
	s_nop 0
	global_load_lds_dwordx4 v[66:67], off
	s_waitcnt vmcnt(8)
	s_waitcnt lgkmcnt(0)
	s_setprio 1
	s_barrier
	v_mfma_f32_16x16x32_bf16 v[66:69], v[2:5], v[34:37], 0
	v_mfma_f32_16x16x32_bf16 v[70:73], v[10:13], v[34:37], 0
	v_mfma_f32_16x16x32_bf16 v[74:77], v[2:5], v[42:45], 0
	v_mfma_f32_16x16x32_bf16 v[78:81], v[10:13], v[42:45], 0
	v_mfma_f32_16x16x32_bf16 v[82:85], v[2:5], v[50:53], 0
	v_mfma_f32_16x16x32_bf16 v[86:89], v[10:13], v[50:53], 0
	v_mfma_f32_16x16x32_bf16 v[90:93], v[2:5], v[58:61], 0
	v_mfma_f32_16x16x32_bf16 v[94:97], v[10:13], v[58:61], 0
	v_mfma_f32_16x16x32_bf16 v[66:69], v[6:9], v[38:41], v[66:69]
	v_mfma_f32_16x16x32_bf16 v[70:73], v[14:17], v[38:41], v[70:73]
	v_mfma_f32_16x16x32_bf16 v[74:77], v[6:9], v[46:49], v[74:77]
	v_mfma_f32_16x16x32_bf16 v[78:81], v[14:17], v[46:49], v[78:81]
	v_mfma_f32_16x16x32_bf16 v[82:85], v[6:9], v[54:57], v[82:85]
	v_mfma_f32_16x16x32_bf16 v[86:89], v[14:17], v[54:57], v[86:89]
	v_mfma_f32_16x16x32_bf16 v[90:93], v[6:9], v[62:65], v[90:93]
	v_mfma_f32_16x16x32_bf16 v[94:97], v[14:17], v[62:65], v[94:97]
	v_mfma_f32_16x16x32_bf16 v[98:101], v[18:21], v[34:37], 0
	v_mfma_f32_16x16x32_bf16 v[34:37], v[26:29], v[34:37], 0
	v_mfma_f32_16x16x32_bf16 v[98:101], v[22:25], v[38:41], v[98:101]
	v_mfma_f32_16x16x32_bf16 v[34:37], v[30:33], v[38:41], v[34:37]
	v_mfma_f32_16x16x32_bf16 v[38:41], v[18:21], v[42:45], 0
	v_mfma_f32_16x16x32_bf16 v[42:45], v[26:29], v[42:45], 0
	v_mfma_f32_16x16x32_bf16 v[38:41], v[22:25], v[46:49], v[38:41]
	v_mfma_f32_16x16x32_bf16 v[42:45], v[30:33], v[46:49], v[42:45]
	v_mfma_f32_16x16x32_bf16 v[46:49], v[18:21], v[50:53], 0
	v_mfma_f32_16x16x32_bf16 v[50:53], v[26:29], v[50:53], 0
	v_mfma_f32_16x16x32_bf16 v[46:49], v[22:25], v[54:57], v[46:49]
	v_mfma_f32_16x16x32_bf16 v[50:53], v[30:33], v[54:57], v[50:53]
	v_mfma_f32_16x16x32_bf16 v[54:57], v[18:21], v[58:61], 0
	v_mfma_f32_16x16x32_bf16 v[58:61], v[26:29], v[58:61], 0
	v_mfma_f32_16x16x32_bf16 v[54:57], v[22:25], v[62:65], v[54:57]
	v_mfma_f32_16x16x32_bf16 v[58:61], v[30:33], v[62:65], v[58:61]
	s_barrier
	s_setprio 0
	s_mov_b32 m0, s52
	v_lshl_add_u64 v[146:147], s[54:55], 0, v[130:131]
	s_add_i32 s15, s52, 0x2000
	ds_read_b128 v[62:65], v144 offset:16384
	ds_read_b128 v[102:105], v144 offset:17408
	ds_read_b128 v[106:109], v144 offset:18432
	ds_read_b128 v[110:113], v144 offset:19456
	ds_read_b128 v[114:117], v144 offset:20480
	ds_read_b128 v[118:121], v144 offset:21504
	ds_read_b128 v[122:125], v144 offset:22528
	ds_read_b128 v[126:129], v144 offset:23552
	global_load_lds_dwordx4 v[146:147], off
	v_lshl_add_u64 v[146:147], s[54:55], 0, v[132:133]
	s_add_u32 s54, s24, 0x11000
	s_mov_b32 m0, s15
	s_addc_u32 s55, s25, 0
	s_add_i32 s17, s48, s38
	global_load_lds_dwordx4 v[146:147], off
	v_lshl_add_u64 v[146:147], s[54:55], 0, v[130:131]
	s_mov_b32 m0, s17
	s_nop 0
	global_load_lds_dwordx4 v[146:147], off
	v_lshl_add_u64 v[146:147], s[54:55], 0, v[132:133]
	s_add_i32 s54, s17, 0x2000
	s_mov_b32 m0, s54
	s_nop 0
	global_load_lds_dwordx4 v[146:147], off
	v_lshl_add_u64 v[146:147], s[34:35], 0, v[130:131]
	s_mov_b32 m0, s19
	s_nop 0
	global_load_lds_dwordx4 v[146:147], off
	v_lshl_add_u64 v[146:147], s[34:35], 0, v[132:133]
	s_mov_b32 m0, s39
	s_nop 0
	global_load_lds_dwordx4 v[146:147], off
	s_waitcnt vmcnt(8)
	s_waitcnt lgkmcnt(0)
	s_setprio 1
	s_barrier
; #define PG8_STAGE(bufoff, gbase, voff) do { _Pragma("unroll") for (int _i = 0; _i < 2; ++_i) \
;         __builtin_amdgcn_global_load_lds((const unsigned*)((const char*)(gbase) + (voff)[_i]), (PG8_LAS unsigned*)(lds + (bufoff) + ldsw + _i * 8192), 16, 0, 0); } while (0)
; #define PG8_LDA(dst, b, h) do { _Pragma("unroll") for (int m = 0; m < 4; ++m) _Pragma("unroll") for (int k = 0; k < 2; ++k) dst[m][k] = *(const PG8_LAS bf16x8*)(lds + PG8_SA(b, h) + aoff + m * 2048 + k * 1024); } while (0)
; #define PG8_LDB(dst, b, h) do { _Pragma("unroll") for (int n = 0; n < 2; ++n) _Pragma("unroll") for (int k = 0; k < 2; ++k) dst[n][k] = *(const PG8_LAS bf16x8*)(lds + PG8_SB(b, h) + boff + n * 2048 + k * 1024); } while (0)
; #define PG8_MMA(ai, bj, At, Bt) do { __builtin_amdgcn_s_setprio(1); _Pragma("unroll") for (int m = 0; m < 4; ++m) _Pragma("unroll") for (int n = 0; n < 2; ++n) _Pragma("unroll") for (int k = 0; k < 2; ++k) \
;         acc[ai][bj][m][n] = __builtin_amdgcn_mfma_f32_16x16x32_bf16(Bt[n][k], At[m][k], acc[ai][bj][m][n], 0, 0, 0); __builtin_amdgcn_s_setprio(0); } while (0)
; #define PG8_WAIT_V(n) asm volatile("s_waitcnt vmcnt(" #n ")" ::: "memory")
; #define PG8_WAIT_L(n) asm volatile("s_waitcnt lgkmcnt(" #n ")" ::: "memory")
; #define PG8_BAR __builtin_amdgcn_s_barrier()
; #define PG8_SCHED __builtin_amdgcn_sched_barrier(0)
; template <class Epi, class Sched, bool ALIGN_EPI, int LMASK = -1, int LMASKB = LMASK>
; __device__ __forceinline__ void gemm_phase(PG8_LAS unsigned char* lds, const Gemm g, const Sched& S, const Epi& E) {
;     ...
;             PG8_WAIT_V(8); PG8_WAIT_L(0); PG8_BAR; PG8_MMA(1, 0, At, B0); PG8_MMA(1, 1, At, B1); PG8_BAR; PG8_SCHED;
;             PG8_LDB(B0, 1, 0); PG8_LDB(B1, 1, 1); PG8_SCHED; PG8_LDA(At, 1, 0); PG8_STAGE(PG8_SA(0, 1), a2 + hstepA, voffA);
;             PG8_WAIT_V(8); PG8_WAIT_L(0); PG8_BAR; PG8_MMA(0, 0, At, B0); PG8_MMA(0, 1, At, B1); PG8_BAR; PG8_SCHED;
	v_mfma_f32_16x16x32_bf16 v[146:149], v[2:5], v[62:65], 0
	v_mfma_f32_16x16x32_bf16 v[154:157], v[2:5], v[106:109], 0
	v_mfma_f32_16x16x32_bf16 v[162:165], v[2:5], v[114:117], 0
	v_mfma_f32_16x16x32_bf16 v[2:5], v[2:5], v[122:125], 0
	v_mfma_f32_16x16x32_bf16 v[146:149], v[6:9], v[102:105], v[146:149]
	v_mfma_f32_16x16x32_bf16 v[154:157], v[6:9], v[110:113], v[154:157]
	v_mfma_f32_16x16x32_bf16 v[162:165], v[6:9], v[118:121], v[162:165]
	v_mfma_f32_16x16x32_bf16 v[2:5], v[6:9], v[126:129], v[2:5]
	v_mfma_f32_16x16x32_bf16 v[6:9], v[10:13], v[122:125], 0
	v_mfma_f32_16x16x32_bf16 v[150:153], v[10:13], v[62:65], 0
	v_mfma_f32_16x16x32_bf16 v[158:161], v[10:13], v[106:109], 0
	v_mfma_f32_16x16x32_bf16 v[166:169], v[10:13], v[114:117], 0
	v_mfma_f32_16x16x32_bf16 v[6:9], v[14:17], v[126:129], v[6:9]
	v_mfma_f32_16x16x32_bf16 v[150:153], v[14:17], v[102:105], v[150:153]
	v_mfma_f32_16x16x32_bf16 v[158:161], v[14:17], v[110:113], v[158:161]
	v_mfma_f32_16x16x32_bf16 v[166:169], v[14:17], v[118:121], v[166:169]
	v_mfma_f32_16x16x32_bf16 v[10:13], v[18:21], v[62:65], 0
	v_mfma_f32_16x16x32_bf16 v[14:17], v[26:29], v[62:65], 0
	v_mfma_f32_16x16x32_bf16 v[10:13], v[22:25], v[102:105], v[10:13]
	v_mfma_f32_16x16x32_bf16 v[14:17], v[30:33], v[102:105], v[14:17]
	v_mfma_f32_16x16x32_bf16 v[62:65], v[18:21], v[106:109], 0
	v_mfma_f32_16x16x32_bf16 v[102:105], v[26:29], v[106:109], 0
	v_mfma_f32_16x16x32_bf16 v[106:109], v[18:21], v[114:117], 0
	v_mfma_f32_16x16x32_bf16 v[18:21], v[18:21], v[122:125], 0
	v_mfma_f32_16x16x32_bf16 v[62:65], v[22:25], v[110:113], v[62:65]
	v_mfma_f32_16x16x32_bf16 v[102:105], v[30:33], v[110:113], v[102:105]
	v_mfma_f32_16x16x32_bf16 v[106:109], v[22:25], v[118:121], v[106:109]
	v_mfma_f32_16x16x32_bf16 v[110:113], v[26:29], v[114:117], 0
	v_mfma_f32_16x16x32_bf16 v[18:21], v[22:25], v[126:129], v[18:21]
	v_mfma_f32_16x16x32_bf16 v[22:25], v[26:29], v[122:125], 0
	v_mfma_f32_16x16x32_bf16 v[110:113], v[30:33], v[118:121], v[110:113]
	v_mfma_f32_16x16x32_bf16 v[22:25], v[30:33], v[126:129], v[22:25]
	s_barrier
	s_setprio 0
	s_add_i32 s55, 0, 0x18000
	s_add_i32 s58, 0, 0x1c000
	v_add_u32_e32 v134, s55, v1
	v_add_u32_e32 v222, s58, v1
	ds_read_b128 v[26:29], v134
	ds_read_b128 v[30:33], v134 offset:1024
	ds_read_b128 v[114:117], v134 offset:2048
	ds_read_b128 v[118:121], v134 offset:3072
	ds_read_b128 v[122:125], v222
	ds_read_b128 v[126:129], v222 offset:1024
	ds_read_b128 v[170:173], v222 offset:2048
	ds_read_b128 v[174:177], v222 offset:3072
	s_add_u32 s34, s22, 0x11000
	s_addc_u32 s35, s23, 0
	s_mov_b32 m0, s40
	v_lshl_add_u64 v[210:211], s[34:35], 0, v[130:131]
	ds_read_b128 v[178:181], v144 offset:32768
	ds_read_b128 v[182:185], v144 offset:33792
	ds_read_b128 v[186:189], v144 offset:34816
	ds_read_b128 v[190:193], v144 offset:35840
	ds_read_b128 v[194:197], v144 offset:36864
	ds_read_b128 v[198:201], v144 offset:37888
	ds_read_b128 v[202:205], v144 offset:38912
	ds_read_b128 v[206:209], v144 offset:39936
	global_load_lds_dwordx4 v[210:211], off
	v_lshl_add_u64 v[210:211], s[34:35], 0, v[132:133]
	s_mov_b32 m0, s41
	s_nop 0
	global_load_lds_dwordx4 v[210:211], off
	s_waitcnt vmcnt(8)
	s_waitcnt lgkmcnt(0)
	s_setprio 1
	s_barrier
	v_mfma_f32_16x16x32_bf16 v[66:69], v[26:29], v[178:181], v[66:69]
	v_mfma_f32_16x16x32_bf16 v[70:73], v[114:117], v[178:181], v[70:73]
	v_mfma_f32_16x16x32_bf16 v[74:77], v[26:29], v[186:189], v[74:77]
	v_mfma_f32_16x16x32_bf16 v[78:81], v[114:117], v[186:189], v[78:81]
	v_mfma_f32_16x16x32_bf16 v[82:85], v[26:29], v[194:197], v[82:85]
	v_mfma_f32_16x16x32_bf16 v[86:89], v[114:117], v[194:197], v[86:89]
	v_mfma_f32_16x16x32_bf16 v[90:93], v[26:29], v[202:205], v[90:93]
	v_mfma_f32_16x16x32_bf16 v[94:97], v[114:117], v[202:205], v[94:97]
	v_mfma_f32_16x16x32_bf16 v[66:69], v[30:33], v[182:185], v[66:69]
	v_mfma_f32_16x16x32_bf16 v[70:73], v[118:121], v[182:185], v[70:73]
	v_mfma_f32_16x16x32_bf16 v[74:77], v[30:33], v[190:193], v[74:77]
	v_mfma_f32_16x16x32_bf16 v[78:81], v[118:121], v[190:193], v[78:81]
	v_mfma_f32_16x16x32_bf16 v[82:85], v[30:33], v[198:201], v[82:85]
	v_mfma_f32_16x16x32_bf16 v[86:89], v[118:121], v[198:201], v[86:89]
	v_mfma_f32_16x16x32_bf16 v[90:93], v[30:33], v[206:209], v[90:93]
	v_mfma_f32_16x16x32_bf16 v[94:97], v[118:121], v[206:209], v[94:97]
	v_mfma_f32_16x16x32_bf16 v[98:101], v[122:125], v[178:181], v[98:101]
	v_mfma_f32_16x16x32_bf16 v[34:37], v[170:173], v[178:181], v[34:37]
	v_mfma_f32_16x16x32_bf16 v[38:41], v[122:125], v[186:189], v[38:41]
	v_mfma_f32_16x16x32_bf16 v[42:45], v[170:173], v[186:189], v[42:45]
	v_mfma_f32_16x16x32_bf16 v[46:49], v[122:125], v[194:197], v[46:49]
	v_mfma_f32_16x16x32_bf16 v[50:53], v[170:173], v[194:197], v[50:53]
	v_mfma_f32_16x16x32_bf16 v[54:57], v[122:125], v[202:205], v[54:57]
	v_mfma_f32_16x16x32_bf16 v[58:61], v[170:173], v[202:205], v[58:61]
	v_mfma_f32_16x16x32_bf16 v[98:101], v[126:129], v[182:185], v[98:101]
	v_mfma_f32_16x16x32_bf16 v[34:37], v[174:177], v[182:185], v[34:37]
	v_mfma_f32_16x16x32_bf16 v[38:41], v[126:129], v[190:193], v[38:41]
	v_mfma_f32_16x16x32_bf16 v[42:45], v[174:177], v[190:193], v[42:45]
	v_mfma_f32_16x16x32_bf16 v[46:49], v[126:129], v[198:201], v[46:49]
	v_mfma_f32_16x16x32_bf16 v[50:53], v[174:177], v[198:201], v[50:53]
	v_mfma_f32_16x16x32_bf16 v[54:57], v[126:129], v[206:209], v[54:57]
	v_mfma_f32_16x16x32_bf16 v[58:61], v[174:177], v[206:209], v[58:61]
	s_barrier
; #define PG8_STAGE(bufoff, gbase, voff) do { _Pragma("unroll") for (int _i = 0; _i < 2; ++_i) \
;         __builtin_amdgcn_global_load_lds((const unsigned*)((const char*)(gbase) + (voff)[_i]), (PG8_LAS unsigned*)(lds + (bufoff) + ldsw + _i * 8192), 16, 0, 0); } while (0)
; #define PG8_LDA(dst, b, h) do { _Pragma("unroll") for (int m = 0; m < 4; ++m) _Pragma("unroll") for (int k = 0; k < 2; ++k) dst[m][k] = *(const PG8_LAS bf16x8*)(lds + PG8_SA(b, h) + aoff + m * 2048 + k * 1024); } while (0)
; #define PG8_LDB(dst, b, h) do { _Pragma("unroll") for (int n = 0; n < 2; ++n) _Pragma("unroll") for (int k = 0; k < 2; ++k) dst[n][k] = *(const PG8_LAS bf16x8*)(lds + PG8_SB(b, h) + boff + n * 2048 + k * 1024); } while (0)
; #define PG8_MMA(ai, bj, At, Bt) do { __builtin_amdgcn_s_setprio(1); _Pragma("unroll") for (int m = 0; m < 4; ++m) _Pragma("unroll") for (int n = 0; n < 2; ++n) _Pragma("unroll") for (int k = 0; k < 2; ++k) \
;         acc[ai][bj][m][n] = __builtin_amdgcn_mfma_f32_16x16x32_bf16(Bt[n][k], At[m][k], acc[ai][bj][m][n], 0, 0, 0); __builtin_amdgcn_s_setprio(0); } while (0)
; #define PG8_BAR __builtin_amdgcn_s_barrier()
; template <class Epi, class Sched, bool ALIGN_EPI, int LMASK = -1, int LMASKB = LMASK>
; __device__ __forceinline__ void gemm_phase(PG8_LAS unsigned char* lds, const Gemm g, const Sched& S, const Epi& E) {
;     ...
;             PG8_LDB(B0, 0, 0); PG8_LDB(B1, 0, 1); PG8_SCHED; PG8_LDA(At, 0, 0); PG8_STAGE(PG8_SA(1, 1), a1 + hstepA, voffA);
;             PG8_WAIT_V(8); PG8_WAIT_L(0); PG8_BAR; PG8_MMA(0, 0, At, B0); PG8_MMA(0, 1, At, B1); PG8_BAR; PG8_SCHED;
;             PG8_LDA(At, 0, 1); PG8_STAGE(PG8_SB(0, 0), b2, voffB); PG8_STAGE(PG8_SB(0, 1), b2 + hstepB, voffB); PG8_STAGE(PG8_SA(0, 0), a2, voffA);
;             PG8_WAIT_V(8); PG8_WAIT_L(0); PG8_BAR; PG8_MMA(1, 0, At, B0); PG8_MMA(1, 1, At, B1); PG8_BAR; PG8_SCHED;
;             PG8_LDB(B0, 1, 0); PG8_LDB(B1, 1, 1); PG8_SCHED; PG8_LDA(At, 1, 0); PG8_STAGE(PG8_SA(0, 1), a2 + hstepA, voffA);
;             PG8_WAIT_V(8); PG8_WAIT_L(0); PG8_BAR; PG8_MMA(0, 0, At, B0); PG8_MMA(0, 1, At, B1); PG8_BAR; PG8_SCHED;
;             PG8_LDA(At, 1, 1); PG8_STAGE(PG8_SB(1, 0), b3, voffB); PG8_STAGE(PG8_SB(1, 1), b3 + hstepB, voffB); PG8_STAGE(PG8_SA(1, 0), a3, voffA);
;             PG8_WAIT_V(8); PG8_WAIT_L(0); PG8_BAR; PG8_MMA(1, 0, At, B0); PG8_MMA(1, 1, At, B1); PG8_BAR; PG8_SCHED;
	s_setprio 0
	s_add_u32 s56, s24, 0x1800
	s_addc_u32 s57, s25, 0
	s_add_i32 s35, s55, s38
	v_lshl_add_u64 v[210:211], s[56:57], 0, v[130:131]
	s_mov_b32 m0, s35
	s_add_i32 s34, s35, 0x2000
	ds_read_b128 v[178:181], v144 offset:49152
	ds_read_b128 v[182:185], v144 offset:50176
	ds_read_b128 v[186:189], v144 offset:51200
	ds_read_b128 v[190:193], v144 offset:52224
	ds_read_b128 v[194:197], v144 offset:53248
	ds_read_b128 v[198:201], v144 offset:54272
	ds_read_b128 v[202:205], v144 offset:55296
	ds_read_b128 v[206:209], v144 offset:56320
	global_load_lds_dwordx4 v[210:211], off
	v_lshl_add_u64 v[210:211], s[56:57], 0, v[132:133]
	s_add_u32 s56, s24, 0x11800
	s_mov_b32 m0, s34
	s_addc_u32 s57, s25, 0
	s_add_i32 s24, s58, s38
	global_load_lds_dwordx4 v[210:211], off
	v_lshl_add_u64 v[210:211], s[56:57], 0, v[130:131]
	s_mov_b32 m0, s24
	s_add_i32 s25, s24, 0x2000
	global_load_lds_dwordx4 v[210:211], off
	v_lshl_add_u64 v[210:211], s[56:57], 0, v[132:133]
	s_mov_b32 m0, s25
	s_nop 0
	global_load_lds_dwordx4 v[210:211], off
	v_lshl_add_u64 v[210:211], s[30:31], 0, v[130:131]
	s_mov_b32 m0, s44
	s_nop 0
	global_load_lds_dwordx4 v[210:211], off
	v_lshl_add_u64 v[210:211], s[30:31], 0, v[132:133]
	s_mov_b32 m0, s45
	s_nop 0
	global_load_lds_dwordx4 v[210:211], off
	s_waitcnt vmcnt(8)
	s_waitcnt lgkmcnt(0)
	s_setprio 1
	s_barrier
	v_mfma_f32_16x16x32_bf16 v[2:5], v[26:29], v[202:205], v[2:5]
	v_mfma_f32_16x16x32_bf16 v[6:9], v[114:117], v[202:205], v[6:9]
	v_mfma_f32_16x16x32_bf16 v[146:149], v[26:29], v[178:181], v[146:149]
	v_mfma_f32_16x16x32_bf16 v[150:153], v[114:117], v[178:181], v[150:153]
	v_mfma_f32_16x16x32_bf16 v[154:157], v[26:29], v[186:189], v[154:157]
	v_mfma_f32_16x16x32_bf16 v[158:161], v[114:117], v[186:189], v[158:161]
	v_mfma_f32_16x16x32_bf16 v[162:165], v[26:29], v[194:197], v[162:165]
	v_mfma_f32_16x16x32_bf16 v[166:169], v[114:117], v[194:197], v[166:169]
	v_mfma_f32_16x16x32_bf16 v[2:5], v[30:33], v[206:209], v[2:5]
	v_mfma_f32_16x16x32_bf16 v[6:9], v[118:121], v[206:209], v[6:9]
	v_mfma_f32_16x16x32_bf16 v[146:149], v[30:33], v[182:185], v[146:149]
	v_mfma_f32_16x16x32_bf16 v[150:153], v[118:121], v[182:185], v[150:153]
	v_mfma_f32_16x16x32_bf16 v[154:157], v[30:33], v[190:193], v[154:157]
	v_mfma_f32_16x16x32_bf16 v[158:161], v[118:121], v[190:193], v[158:161]
	v_mfma_f32_16x16x32_bf16 v[162:165], v[30:33], v[198:201], v[162:165]
	v_mfma_f32_16x16x32_bf16 v[166:169], v[118:121], v[198:201], v[166:169]
	v_mfma_f32_16x16x32_bf16 v[10:13], v[122:125], v[178:181], v[10:13]
	v_mfma_f32_16x16x32_bf16 v[14:17], v[170:173], v[178:181], v[14:17]
	v_mfma_f32_16x16x32_bf16 v[26:29], v[122:125], v[186:189], v[62:65]
	v_mfma_f32_16x16x32_bf16 v[30:33], v[170:173], v[186:189], v[102:105]
	v_mfma_f32_16x16x32_bf16 v[62:65], v[122:125], v[194:197], v[106:109]
	v_mfma_f32_16x16x32_bf16 v[102:105], v[170:173], v[194:197], v[110:113]
	v_mfma_f32_16x16x32_bf16 v[18:21], v[122:125], v[202:205], v[18:21]
	v_mfma_f32_16x16x32_bf16 v[22:25], v[170:173], v[202:205], v[22:25]
	v_mfma_f32_16x16x32_bf16 v[10:13], v[126:129], v[182:185], v[10:13]
	v_mfma_f32_16x16x32_bf16 v[14:17], v[174:177], v[182:185], v[14:17]
	v_mfma_f32_16x16x32_bf16 v[26:29], v[126:129], v[190:193], v[26:29]
	v_mfma_f32_16x16x32_bf16 v[30:33], v[174:177], v[190:193], v[30:33]
	v_mfma_f32_16x16x32_bf16 v[62:65], v[126:129], v[198:201], v[62:65]
	v_mfma_f32_16x16x32_bf16 v[102:105], v[174:177], v[198:201], v[102:105]
	v_mfma_f32_16x16x32_bf16 v[18:21], v[126:129], v[206:209], v[18:21]
	v_mfma_f32_16x16x32_bf16 v[22:25], v[174:177], v[206:209], v[22:25]
	s_barrier
	s_setprio 0
	ds_read_b128 v[106:109], v142
	ds_read_b128 v[110:113], v142 offset:1024
	ds_read_b128 v[114:117], v142 offset:2048
	ds_read_b128 v[118:121], v142 offset:3072
	ds_read_b128 v[122:125], v143
	ds_read_b128 v[126:129], v143 offset:1024
	ds_read_b128 v[170:173], v143 offset:2048
	ds_read_b128 v[174:177], v143 offset:3072
	s_add_u32 s22, s22, 0x11800
	s_addc_u32 s23, s23, 0
	s_mov_b32 m0, s50
	v_lshl_add_u64 v[210:211], s[22:23], 0, v[130:131]
	ds_read_b128 v[178:181], v144
	ds_read_b128 v[182:185], v144 offset:1024
	ds_read_b128 v[186:189], v144 offset:2048
	ds_read_b128 v[190:193], v144 offset:3072
	ds_read_b128 v[194:197], v144 offset:4096
	ds_read_b128 v[198:201], v144 offset:5120
	ds_read_b128 v[202:205], v144 offset:6144
	ds_read_b128 v[206:209], v144 offset:7168
	global_load_lds_dwordx4 v[210:211], off
	v_lshl_add_u64 v[210:211], s[22:23], 0, v[132:133]
	s_mov_b32 m0, s51
	s_nop 0
	global_load_lds_dwordx4 v[210:211], off
	s_waitcnt vmcnt(8)
	s_waitcnt lgkmcnt(0)
	s_setprio 1
	s_barrier
; #define PG8_STAGE(bufoff, gbase, voff) do { _Pragma("unroll") for (int _i = 0; _i < 2; ++_i) \
;         __builtin_amdgcn_global_load_lds((const unsigned*)((const char*)(gbase) + (voff)[_i]), (PG8_LAS unsigned*)(lds + (bufoff) + ldsw + _i * 8192), 16, 0, 0); } while (0)
; #define PG8_LDA(dst, b, h) do { _Pragma("unroll") for (int m = 0; m < 4; ++m) _Pragma("unroll") for (int k = 0; k < 2; ++k) dst[m][k] = *(const PG8_LAS bf16x8*)(lds + PG8_SA(b, h) + aoff + m * 2048 + k * 1024); } while (0)
; #define PG8_MMA(ai, bj, At, Bt) do { __builtin_amdgcn_s_setprio(1); _Pragma("unroll") for (int m = 0; m < 4; ++m) _Pragma("unroll") for (int n = 0; n < 2; ++n) _Pragma("unroll") for (int k = 0; k < 2; ++k) \
;         acc[ai][bj][m][n] = __builtin_amdgcn_mfma_f32_16x16x32_bf16(Bt[n][k], At[m][k], acc[ai][bj][m][n], 0, 0, 0); __builtin_amdgcn_s_setprio(0); } while (0)
; #define PG8_WAIT_V(n) asm volatile("s_waitcnt vmcnt(" #n ")" ::: "memory")
; #define PG8_WAIT_L(n) asm volatile("s_waitcnt lgkmcnt(" #n ")" ::: "memory")
; #define PG8_BAR __builtin_amdgcn_s_barrier()
; #define PG8_SCHED __builtin_amdgcn_sched_barrier(0)
; template <class Epi, class Sched, bool ALIGN_EPI, int LMASK = -1, int LMASKB = LMASK>
; __device__ __forceinline__ void gemm_phase(PG8_LAS unsigned char* lds, const Gemm g, const Sched& S, const Epi& E) {
;     ...
;             PG8_WAIT_V(8); PG8_WAIT_L(0); PG8_BAR; PG8_MMA(0, 0, At, B0); PG8_MMA(0, 1, At, B1); PG8_BAR; PG8_SCHED;
;             PG8_LDA(At, 0, 1); PG8_STAGE(PG8_SB(0, 0), b2, voffB); PG8_STAGE(PG8_SB(0, 1), b2 + hstepB, voffB); PG8_STAGE(PG8_SA(0, 0), a2, voffA);
;             PG8_WAIT_V(8); PG8_WAIT_L(0); PG8_BAR; PG8_MMA(1, 0, At, B0); PG8_MMA(1, 1, At, B1); PG8_BAR; PG8_SCHED;
	v_mfma_f32_16x16x32_bf16 v[66:69], v[106:109], v[178:181], v[66:69]
	v_mfma_f32_16x16x32_bf16 v[70:73], v[114:117], v[178:181], v[70:73]
	v_mfma_f32_16x16x32_bf16 v[74:77], v[106:109], v[186:189], v[74:77]
	v_mfma_f32_16x16x32_bf16 v[78:81], v[114:117], v[186:189], v[78:81]
	v_mfma_f32_16x16x32_bf16 v[82:85], v[106:109], v[194:197], v[82:85]
	v_mfma_f32_16x16x32_bf16 v[86:89], v[114:117], v[194:197], v[86:89]
	v_mfma_f32_16x16x32_bf16 v[90:93], v[106:109], v[202:205], v[90:93]
	v_mfma_f32_16x16x32_bf16 v[94:97], v[114:117], v[202:205], v[94:97]
	v_mfma_f32_16x16x32_bf16 v[66:69], v[110:113], v[182:185], v[66:69]
	v_mfma_f32_16x16x32_bf16 v[70:73], v[118:121], v[182:185], v[70:73]
	v_mfma_f32_16x16x32_bf16 v[74:77], v[110:113], v[190:193], v[74:77]
	v_mfma_f32_16x16x32_bf16 v[78:81], v[118:121], v[190:193], v[78:81]
	v_mfma_f32_16x16x32_bf16 v[82:85], v[110:113], v[198:201], v[82:85]
	v_mfma_f32_16x16x32_bf16 v[86:89], v[118:121], v[198:201], v[86:89]
	v_mfma_f32_16x16x32_bf16 v[90:93], v[110:113], v[206:209], v[90:93]
	v_mfma_f32_16x16x32_bf16 v[94:97], v[118:121], v[206:209], v[94:97]
	v_mfma_f32_16x16x32_bf16 v[34:37], v[170:173], v[178:181], v[34:37]
	v_mfma_f32_16x16x32_bf16 v[98:101], v[122:125], v[178:181], v[98:101]
	v_mfma_f32_16x16x32_bf16 v[178:181], v[174:177], v[182:185], v[34:37]
	v_mfma_f32_16x16x32_bf16 v[34:37], v[122:125], v[186:189], v[38:41]
	v_mfma_f32_16x16x32_bf16 v[210:213], v[126:129], v[182:185], v[98:101]
	v_mfma_f32_16x16x32_bf16 v[182:185], v[126:129], v[190:193], v[34:37]
	v_mfma_f32_16x16x32_bf16 v[34:37], v[170:173], v[186:189], v[42:45]
	v_mfma_f32_16x16x32_bf16 v[42:45], v[174:177], v[190:193], v[34:37]
	v_mfma_f32_16x16x32_bf16 v[34:37], v[122:125], v[194:197], v[46:49]
	v_mfma_f32_16x16x32_bf16 v[46:49], v[126:129], v[198:201], v[34:37]
	v_mfma_f32_16x16x32_bf16 v[34:37], v[170:173], v[194:197], v[50:53]
	v_mfma_f32_16x16x32_bf16 v[50:53], v[174:177], v[198:201], v[34:37]
	v_mfma_f32_16x16x32_bf16 v[34:37], v[122:125], v[202:205], v[54:57]
	v_mfma_f32_16x16x32_bf16 v[54:57], v[126:129], v[206:209], v[34:37]
	v_mfma_f32_16x16x32_bf16 v[34:37], v[170:173], v[202:205], v[58:61]
	v_mfma_f32_16x16x32_bf16 v[58:61], v[174:177], v[206:209], v[34:37]
	s_barrier
	s_setprio 0
	s_mov_b32 m0, s52
	v_lshl_add_u64 v[246:247], s[26:27], 0, v[130:131]
	s_add_u32 s22, s26, 0x10000
	s_nop 1
	ds_read_b128 v[34:37], v144 offset:16384
	ds_read_b128 v[38:41], v144 offset:17408
	ds_read_b128 v[98:101], v144 offset:18432
	ds_read_b128 v[186:189], v144 offset:19456
	ds_read_b128 v[190:193], v144 offset:20480
	ds_read_b128 v[194:197], v144 offset:21504
	ds_read_b128 v[198:201], v144 offset:22528
	ds_read_b128 v[202:205], v144 offset:23552
	global_load_lds_dwordx4 v[246:247], off
	v_lshl_add_u64 v[248:249], s[26:27], 0, v[132:133]
	s_mov_b32 m0, s15
	s_addc_u32 s23, s27, 0
	global_load_lds_dwordx4 v[248:249], off
	v_lshl_add_u64 v[206:207], s[22:23], 0, v[130:131]
	s_mov_b32 m0, s17
	v_lshl_add_u64 v[250:251], s[28:29], 0, v[130:131]
	global_load_lds_dwordx4 v[206:207], off
	v_lshl_add_u64 v[206:207], s[22:23], 0, v[132:133]
	s_mov_b32 m0, s54
	v_lshl_add_u64 v[252:253], s[28:29], 0, v[132:133]
	global_load_lds_dwordx4 v[206:207], off
	s_mov_b32 m0, s19
	s_nop 0
	global_load_lds_dwordx4 v[250:251], off
	s_mov_b32 m0, s39
	s_nop 0
	global_load_lds_dwordx4 v[252:253], off
	s_waitcnt vmcnt(8)
	s_waitcnt lgkmcnt(0)
	s_setprio 1
	s_barrier
	v_mfma_f32_16x16x32_bf16 v[2:5], v[106:109], v[198:201], v[2:5]
	v_mfma_f32_16x16x32_bf16 v[6:9], v[114:117], v[198:201], v[6:9]
	v_mfma_f32_16x16x32_bf16 v[146:149], v[106:109], v[34:37], v[146:149]
	v_mfma_f32_16x16x32_bf16 v[150:153], v[114:117], v[34:37], v[150:153]
	v_mfma_f32_16x16x32_bf16 v[154:157], v[106:109], v[98:101], v[154:157]
	v_mfma_f32_16x16x32_bf16 v[158:161], v[114:117], v[98:101], v[158:161]
	v_mfma_f32_16x16x32_bf16 v[162:165], v[106:109], v[190:193], v[162:165]
	v_mfma_f32_16x16x32_bf16 v[166:169], v[114:117], v[190:193], v[166:169]
	v_mfma_f32_16x16x32_bf16 v[2:5], v[110:113], v[202:205], v[2:5]
	v_mfma_f32_16x16x32_bf16 v[6:9], v[118:121], v[202:205], v[6:9]
	v_mfma_f32_16x16x32_bf16 v[146:149], v[110:113], v[38:41], v[146:149]
	v_mfma_f32_16x16x32_bf16 v[150:153], v[118:121], v[38:41], v[150:153]
	v_mfma_f32_16x16x32_bf16 v[154:157], v[110:113], v[186:189], v[154:157]
	v_mfma_f32_16x16x32_bf16 v[158:161], v[118:121], v[186:189], v[158:161]
	v_mfma_f32_16x16x32_bf16 v[162:165], v[110:113], v[194:197], v[162:165]
	v_mfma_f32_16x16x32_bf16 v[166:169], v[118:121], v[194:197], v[166:169]
	v_mfma_f32_16x16x32_bf16 v[10:13], v[122:125], v[34:37], v[10:13]
	v_mfma_f32_16x16x32_bf16 v[14:17], v[170:173], v[34:37], v[14:17]
	v_mfma_f32_16x16x32_bf16 v[26:29], v[122:125], v[98:101], v[26:29]
	v_mfma_f32_16x16x32_bf16 v[30:33], v[170:173], v[98:101], v[30:33]
	v_mfma_f32_16x16x32_bf16 v[34:37], v[122:125], v[190:193], v[62:65]
	v_mfma_f32_16x16x32_bf16 v[26:29], v[126:129], v[186:189], v[26:29]
	v_mfma_f32_16x16x32_bf16 v[30:33], v[174:177], v[186:189], v[30:33]
	v_mfma_f32_16x16x32_bf16 v[186:189], v[126:129], v[194:197], v[34:37]
	v_mfma_f32_16x16x32_bf16 v[34:37], v[170:173], v[190:193], v[102:105]
	v_mfma_f32_16x16x32_bf16 v[18:21], v[122:125], v[198:201], v[18:21]
	v_mfma_f32_16x16x32_bf16 v[10:13], v[126:129], v[38:41], v[10:13]
	v_mfma_f32_16x16x32_bf16 v[14:17], v[174:177], v[38:41], v[14:17]
	v_mfma_f32_16x16x32_bf16 v[190:193], v[174:177], v[194:197], v[34:37]
	v_mfma_f32_16x16x32_bf16 v[194:197], v[126:129], v[202:205], v[18:21]
	v_mfma_f32_16x16x32_bf16 v[18:21], v[170:173], v[198:201], v[22:25]
	v_mfma_f32_16x16x32_bf16 v[170:173], v[174:177], v[202:205], v[18:21]
	s_barrier
; #define PG8_STAGE(bufoff, gbase, voff) do { _Pragma("unroll") for (int _i = 0; _i < 2; ++_i) \
;         __builtin_amdgcn_global_load_lds((const unsigned*)((const char*)(gbase) + (voff)[_i]), (PG8_LAS unsigned*)(lds + (bufoff) + ldsw + _i * 8192), 16, 0, 0); } while (0)
; #define PG8_LDA(dst, b, h) do { _Pragma("unroll") for (int m = 0; m < 4; ++m) _Pragma("unroll") for (int k = 0; k < 2; ++k) dst[m][k] = *(const PG8_LAS bf16x8*)(lds + PG8_SA(b, h) + aoff + m * 2048 + k * 1024); } while (0)
; #define PG8_LDB(dst, b, h) do { _Pragma("unroll") for (int n = 0; n < 2; ++n) _Pragma("unroll") for (int k = 0; k < 2; ++k) dst[n][k] = *(const PG8_LAS bf16x8*)(lds + PG8_SB(b, h) + boff + n * 2048 + k * 1024); } while (0)
; #define PG8_MMA(ai, bj, At, Bt) do { __builtin_amdgcn_s_setprio(1); _Pragma("unroll") for (int m = 0; m < 4; ++m) _Pragma("unroll") for (int n = 0; n < 2; ++n) _Pragma("unroll") for (int k = 0; k < 2; ++k) \
;         acc[ai][bj][m][n] = __builtin_amdgcn_mfma_f32_16x16x32_bf16(Bt[n][k], At[m][k], acc[ai][bj][m][n], 0, 0, 0); __builtin_amdgcn_s_setprio(0); } while (0)
; #define PG8_WAIT_V(n) asm volatile("s_waitcnt vmcnt(" #n ")" ::: "memory")
; #define PG8_WAIT_L(n) asm volatile("s_waitcnt lgkmcnt(" #n ")" ::: "memory")
; #define PG8_BAR __builtin_amdgcn_s_barrier()
; #define PG8_SCHED __builtin_amdgcn_sched_barrier(0)
; template <class Epi, class Sched, bool ALIGN_EPI, int LMASK = -1, int LMASKB = LMASK>
; __device__ __forceinline__ void gemm_phase(PG8_LAS unsigned char* lds, const Gemm g, const Sched& S, const Epi& E) {
;     ...
;             PG8_LDB(B0, 1, 0); PG8_LDB(B1, 1, 1); PG8_SCHED; PG8_LDA(At, 1, 0); PG8_STAGE(PG8_SA(0, 1), a2 + hstepA, voffA);
;             PG8_WAIT_V(8); PG8_WAIT_L(0); PG8_BAR; PG8_MMA(0, 0, At, B0); PG8_MMA(0, 1, At, B1); PG8_BAR; PG8_SCHED;
;             PG8_LDA(At, 1, 1); PG8_STAGE(PG8_SB(1, 0), b3, voffB); PG8_STAGE(PG8_SB(1, 1), b3 + hstepB, voffB); PG8_STAGE(PG8_SA(1, 0), a3, voffA);
;             PG8_WAIT_V(8); PG8_WAIT_L(0); PG8_BAR; PG8_MMA(1, 0, At, B0); PG8_MMA(1, 1, At, B1); PG8_BAR; PG8_SCHED;
;         }
;         if constexpr (ALIGN_EPI) { if (wr == 0) PG8_BAR; }
;         E(acc, cur, wr, wc, fr, fq);
;         if (!has_next) break;
	s_setprio 0
	ds_read_b128 v[62:65], v134
	ds_read_b128 v[174:177], v134 offset:1024
	ds_read_b128 v[198:201], v134 offset:2048
	ds_read_b128 v[202:205], v134 offset:3072
	ds_read_b128 v[206:209], v222
	ds_read_b128 v[214:217], v222 offset:1024
	ds_read_b128 v[218:221], v222 offset:2048
	ds_read_b128 v[222:225], v222 offset:3072
	s_add_u32 s22, s28, 0x10000
	s_addc_u32 s23, s29, 0
	s_mov_b32 m0, s40
	v_lshl_add_u64 v[34:35], s[22:23], 0, v[130:131]
	ds_read_b128 v[18:21], v144 offset:32768
	ds_read_b128 v[22:25], v144 offset:33792
	ds_read_b128 v[110:113], v144 offset:34816
	ds_read_b128 v[226:229], v144 offset:35840
	ds_read_b128 v[230:233], v144 offset:36864
	ds_read_b128 v[234:237], v144 offset:37888
	ds_read_b128 v[238:241], v144 offset:38912
	ds_read_b128 v[242:245], v144 offset:39936
	global_load_lds_dwordx4 v[34:35], off
	v_lshl_add_u64 v[34:35], s[22:23], 0, v[132:133]
	s_mov_b32 m0, s41
	s_nop 0
	global_load_lds_dwordx4 v[34:35], off
	s_waitcnt vmcnt(8)
	s_waitcnt lgkmcnt(0)
	s_setprio 1
	s_barrier
	v_mfma_f32_16x16x32_bf16 v[34:37], v[62:65], v[18:21], v[66:69]
	v_mfma_f32_16x16x32_bf16 v[114:117], v[174:177], v[22:25], v[34:37]
	v_mfma_f32_16x16x32_bf16 v[34:37], v[198:201], v[18:21], v[70:73]
	v_mfma_f32_16x16x32_bf16 v[118:121], v[202:205], v[22:25], v[34:37]
	v_mfma_f32_16x16x32_bf16 v[34:37], v[62:65], v[110:113], v[74:77]
	v_mfma_f32_16x16x32_bf16 v[98:101], v[174:177], v[226:229], v[34:37]
	v_mfma_f32_16x16x32_bf16 v[34:37], v[198:201], v[110:113], v[78:81]
	v_mfma_f32_16x16x32_bf16 v[102:105], v[202:205], v[226:229], v[34:37]
	v_mfma_f32_16x16x32_bf16 v[34:37], v[62:65], v[230:233], v[82:85]
	v_mfma_f32_16x16x32_bf16 v[66:69], v[174:177], v[234:237], v[34:37]
	v_mfma_f32_16x16x32_bf16 v[34:37], v[198:201], v[230:233], v[86:89]
	v_mfma_f32_16x16x32_bf16 v[70:73], v[202:205], v[234:237], v[34:37]
	v_mfma_f32_16x16x32_bf16 v[34:37], v[62:65], v[238:241], v[90:93]
	v_mfma_f32_16x16x32_bf16 v[38:41], v[198:201], v[238:241], v[94:97]
	v_mfma_f32_16x16x32_bf16 v[34:37], v[174:177], v[242:245], v[34:37]
	v_mfma_f32_16x16x32_bf16 v[38:41], v[202:205], v[242:245], v[38:41]
	v_mfma_f32_16x16x32_bf16 v[74:77], v[206:209], v[18:21], v[210:213]
	v_mfma_f32_16x16x32_bf16 v[18:21], v[218:221], v[18:21], v[178:181]
	v_mfma_f32_16x16x32_bf16 v[126:129], v[222:225], v[22:25], v[18:21]
	v_mfma_f32_16x16x32_bf16 v[18:21], v[206:209], v[110:113], v[182:185]
	v_mfma_f32_16x16x32_bf16 v[106:109], v[214:217], v[226:229], v[18:21]
	v_mfma_f32_16x16x32_bf16 v[18:21], v[218:221], v[110:113], v[42:45]
	v_mfma_f32_16x16x32_bf16 v[110:113], v[222:225], v[226:229], v[18:21]
	v_mfma_f32_16x16x32_bf16 v[18:21], v[206:209], v[230:233], v[46:49]
	v_mfma_f32_16x16x32_bf16 v[122:125], v[214:217], v[22:25], v[74:77]
	v_mfma_f32_16x16x32_bf16 v[74:77], v[214:217], v[234:237], v[18:21]
	v_mfma_f32_16x16x32_bf16 v[18:21], v[218:221], v[230:233], v[50:53]
	v_mfma_f32_16x16x32_bf16 v[78:81], v[222:225], v[234:237], v[18:21]
	v_mfma_f32_16x16x32_bf16 v[18:21], v[206:209], v[238:241], v[54:57]
	v_mfma_f32_16x16x32_bf16 v[42:45], v[214:217], v[242:245], v[18:21]
	v_mfma_f32_16x16x32_bf16 v[18:21], v[218:221], v[238:241], v[58:61]
	v_mfma_f32_16x16x32_bf16 v[46:49], v[222:225], v[242:245], v[18:21]
	s_barrier
	s_setprio 0
	s_mov_b32 m0, s35
	s_nop 3
	v_lshl_add_u64 v[18:19], v[246:247], 0, s[8:9]
	s_add_u32 s22, s26, 0x10800
	ds_read_b128 v[58:61], v144 offset:49152
	ds_read_b128 v[94:97], v144 offset:50176
	ds_read_b128 v[178:181], v144 offset:51200
	ds_read_b128 v[182:185], v144 offset:52224
	ds_read_b128 v[210:213], v144 offset:53248
	ds_read_b128 v[226:229], v144 offset:54272
	ds_read_b128 v[230:233], v144 offset:55296
	ds_read_b128 v[234:237], v144 offset:56320
	global_load_lds_dwordx4 v[18:19], off
	v_lshl_add_u64 v[18:19], v[248:249], 0, s[8:9]
	s_mov_b32 m0, s34
	s_addc_u32 s23, s27, 0
	global_load_lds_dwordx4 v[18:19], off
	v_lshl_add_u64 v[18:19], s[22:23], 0, v[130:131]
	s_mov_b32 m0, s24
	s_nop 0
	global_load_lds_dwordx4 v[18:19], off
	v_lshl_add_u64 v[18:19], s[22:23], 0, v[132:133]
	s_mov_b32 m0, s25
	s_nop 0
	global_load_lds_dwordx4 v[18:19], off
	v_lshl_add_u64 v[18:19], v[250:251], 0, s[8:9]
	s_mov_b32 m0, s44
	s_nop 0
	global_load_lds_dwordx4 v[18:19], off
	v_lshl_add_u64 v[18:19], v[252:253], 0, s[8:9]
	s_mov_b32 m0, s45
	s_nop 0
	global_load_lds_dwordx4 v[18:19], off
	s_waitcnt vmcnt(8)
	s_waitcnt lgkmcnt(0)
	s_setprio 1
	s_barrier
	v_mfma_f32_16x16x32_bf16 v[18:21], v[62:65], v[58:61], v[146:149]
	v_mfma_f32_16x16x32_bf16 v[82:85], v[174:177], v[94:97], v[18:21]
	v_mfma_f32_16x16x32_bf16 v[18:21], v[198:201], v[58:61], v[150:153]
	v_mfma_f32_16x16x32_bf16 v[86:89], v[202:205], v[94:97], v[18:21]
	v_mfma_f32_16x16x32_bf16 v[18:21], v[62:65], v[178:181], v[154:157]
	v_mfma_f32_16x16x32_bf16 v[50:53], v[174:177], v[182:185], v[18:21]
	v_mfma_f32_16x16x32_bf16 v[18:21], v[198:201], v[178:181], v[158:161]
	v_mfma_f32_16x16x32_bf16 v[54:57], v[202:205], v[182:185], v[18:21]
	v_mfma_f32_16x16x32_bf16 v[18:21], v[62:65], v[210:213], v[162:165]
	v_mfma_f32_16x16x32_bf16 v[22:25], v[198:201], v[210:213], v[166:169]
	v_mfma_f32_16x16x32_bf16 v[2:5], v[62:65], v[230:233], v[2:5]
	v_mfma_f32_16x16x32_bf16 v[6:9], v[198:201], v[230:233], v[6:9]
	v_mfma_f32_16x16x32_bf16 v[18:21], v[174:177], v[226:229], v[18:21]
	v_mfma_f32_16x16x32_bf16 v[22:25], v[202:205], v[226:229], v[22:25]
	v_mfma_f32_16x16x32_bf16 v[2:5], v[174:177], v[234:237], v[2:5]
	v_mfma_f32_16x16x32_bf16 v[6:9], v[202:205], v[234:237], v[6:9]
	v_mfma_f32_16x16x32_bf16 v[10:13], v[206:209], v[58:61], v[10:13]
	v_mfma_f32_16x16x32_bf16 v[90:93], v[214:217], v[94:97], v[10:13]
	v_mfma_f32_16x16x32_bf16 v[10:13], v[218:221], v[58:61], v[14:17]
	v_mfma_f32_16x16x32_bf16 v[94:97], v[222:225], v[94:97], v[10:13]
	v_mfma_f32_16x16x32_bf16 v[10:13], v[206:209], v[178:181], v[26:29]
	v_mfma_f32_16x16x32_bf16 v[58:61], v[214:217], v[182:185], v[10:13]
	v_mfma_f32_16x16x32_bf16 v[10:13], v[218:221], v[178:181], v[30:33]
	v_mfma_f32_16x16x32_bf16 v[62:65], v[222:225], v[182:185], v[10:13]
	v_mfma_f32_16x16x32_bf16 v[10:13], v[206:209], v[210:213], v[186:189]
	v_mfma_f32_16x16x32_bf16 v[26:29], v[214:217], v[226:229], v[10:13]
	v_mfma_f32_16x16x32_bf16 v[10:13], v[218:221], v[210:213], v[190:193]
	v_mfma_f32_16x16x32_bf16 v[30:33], v[222:225], v[226:229], v[10:13]
	v_mfma_f32_16x16x32_bf16 v[10:13], v[206:209], v[230:233], v[194:197]
	v_mfma_f32_16x16x32_bf16 v[14:17], v[218:221], v[230:233], v[170:173]
	v_mfma_f32_16x16x32_bf16 v[10:13], v[214:217], v[234:237], v[10:13]
	v_mfma_f32_16x16x32_bf16 v[14:17], v[222:225], v[234:237], v[14:17]
	s_barrier
	s_setprio 0
	s_andn2_b64 vcc, exec, s[10:11]
	s_cbranch_vccnz .LBB0_208
	s_barrier

; #define PG8_STAGE(bufoff, gbase, voff) do { _Pragma("unroll") for (int _i = 0; _i < 2; ++_i) \
;         __builtin_amdgcn_global_load_lds((const unsigned*)((const char*)(gbase) + (voff)[_i]), (PG8_LAS unsigned*)(lds + (bufoff) + ldsw + _i * 8192), 16, 0, 0); } while (0)
; #define PG8_LDA(dst, b, h) do { _Pragma("unroll") for (int m = 0; m < 4; ++m) _Pragma("unroll") for (int k = 0; k < 2; ++k) dst[m][k] = *(const PG8_LAS bf16x8*)(lds + PG8_SA(b, h) + aoff + m * 2048 + k * 1024); } while (0)
; #define PG8_LDB(dst, b, h) do { _Pragma("unroll") for (int n = 0; n < 2; ++n) _Pragma("unroll") for (int k = 0; k < 2; ++k) dst[n][k] = *(const PG8_LAS bf16x8*)(lds + PG8_SB(b, h) + boff + n * 2048 + k * 1024); } while (0)
; #define PG8_MMA(ai, bj, At, Bt) do { __builtin_amdgcn_s_setprio(1); _Pragma("unroll") for (int m = 0; m < 4; ++m) _Pragma("unroll") for (int n = 0; n < 2; ++n) _Pragma("unroll") for (int k = 0; k < 2; ++k) \
;         acc[ai][bj][m][n] = __builtin_amdgcn_mfma_f32_16x16x32_bf16(Bt[n][k], At[m][k], acc[ai][bj][m][n], 0, 0, 0); __builtin_amdgcn_s_setprio(0); } while (0)
; #define PG8_WAIT_V(n) asm volatile("s_waitcnt vmcnt(" #n ")" ::: "memory")
; #define PG8_WAIT_L(n) asm volatile("s_waitcnt lgkmcnt(" #n ")" ::: "memory")
; #define PG8_BAR __builtin_amdgcn_s_barrier()
; #define PG8_SCHED __builtin_amdgcn_sched_barrier(0)
; template <class Epi, class Sched, bool ALIGN_EPI, int LMASK = -1, int LMASKB = LMASK>
; __device__ __forceinline__ void gemm_phase(PG8_LAS unsigned char* lds, const Gemm g, const Sched& S, const Epi& E) {
;     ...
;             const bool last = (t == nt - 2);
;             const char* a1 = cA + (size_t)(t + 1) * kstepA;
;             const char* a2 = last ? nA : cA + (size_t)(t + 2) * kstepA; const char* b2 = last ? nB : cB + (size_t)(t + 2) * kstepB;
;             const char* a3 = a2 + kstepA; const char* b3 = b2 + kstepB;
;             PG8_LDB(B0, 0, 0); PG8_LDB(B1, 0, 1); PG8_SCHED; PG8_LDA(At, 0, 0); PG8_STAGE(PG8_SA(1, 1), a1 + hstepA, voffA);
;             PG8_WAIT_V(8); PG8_WAIT_L(0); PG8_BAR; PG8_MMA(0, 0, At, B0); PG8_MMA(0, 1, At, B1); PG8_BAR; PG8_SCHED;
;             PG8_LDA(At, 0, 1); PG8_STAGE(PG8_SB(0, 0), b2, voffB); PG8_STAGE(PG8_SB(0, 1), b2 + hstepB, voffB); PG8_STAGE(PG8_SA(0, 0), a2, voffA);
.LBB0_284:
	s_add_u32 s10, s8, 0xfff00800
	s_addc_u32 s11, s9, -1
	s_add_i32 s55, 0, 0x10000
	s_cmp_eq_u32 s54, 60
	s_cselect_b32 s37, s0, s11
	s_cselect_b32 s36, s1, s10
	s_cselect_b32 s11, s2, s29
	s_cselect_b32 s10, s7, s27
	s_add_i32 s58, 0, 0x14000
	v_add_u32_e32 v142, s55, v161
	v_add_u32_e32 v154, s58, v161
	ds_read_b128 v[130:133], v142
	ds_read_b128 v[134:137], v142 offset:1024
	ds_read_b128 v[138:141], v142 offset:2048
	ds_read_b128 v[142:145], v142 offset:3072
	ds_read_b128 v[172:175], v154
	ds_read_b128 v[188:191], v154 offset:1024
	ds_read_b128 v[218:221], v154 offset:2048
	ds_read_b128 v[222:225], v154 offset:3072
	v_lshl_add_u64 v[154:155], s[8:9], 0, v[150:151]
	s_add_i32 m0, s45, 0xc000
	ds_read_b128 v[226:229], v171
	ds_read_b128 v[230:233], v171 offset:1024
	ds_read_b128 v[234:237], v171 offset:2048
	ds_read_b128 v[238:241], v171 offset:3072
	ds_read_b128 v[242:245], v171 offset:4096
	ds_read_b128 v[246:249], v171 offset:5120
	ds_read_b128 v[250:253], v171 offset:6144
	ds_read_b128 v[206:209], v171 offset:7168
	global_load_lds_dwordx4 v[154:155], off
	v_lshl_add_u64 v[154:155], s[8:9], 0, v[152:153]
	s_add_i32 m0, s45, 0xe000
	s_nop 0
	global_load_lds_dwordx4 v[154:155], off
	s_waitcnt vmcnt(8)
	s_waitcnt lgkmcnt(0)
	s_setprio 1
	s_barrier
	v_mfma_f32_16x16x32_bf16 v[126:129], v[130:133], v[226:229], v[126:129]
	v_mfma_f32_16x16x32_bf16 v[122:125], v[138:141], v[226:229], v[122:125]
	v_mfma_f32_16x16x32_bf16 v[118:121], v[130:133], v[234:237], v[118:121]
	v_mfma_f32_16x16x32_bf16 v[110:113], v[138:141], v[234:237], v[110:113]
	v_mfma_f32_16x16x32_bf16 v[102:105], v[130:133], v[242:245], v[102:105]
	v_mfma_f32_16x16x32_bf16 v[94:97], v[138:141], v[242:245], v[94:97]
	v_mfma_f32_16x16x32_bf16 v[86:89], v[130:133], v[250:253], v[86:89]
	v_mfma_f32_16x16x32_bf16 v[78:81], v[138:141], v[250:253], v[78:81]
	v_mfma_f32_16x16x32_bf16 v[126:129], v[134:137], v[230:233], v[126:129]
	v_mfma_f32_16x16x32_bf16 v[122:125], v[142:145], v[230:233], v[122:125]
	v_mfma_f32_16x16x32_bf16 v[118:121], v[134:137], v[238:241], v[118:121]
	v_mfma_f32_16x16x32_bf16 v[110:113], v[142:145], v[238:241], v[110:113]
	v_mfma_f32_16x16x32_bf16 v[102:105], v[134:137], v[246:249], v[102:105]
	v_mfma_f32_16x16x32_bf16 v[94:97], v[142:145], v[246:249], v[94:97]
	v_mfma_f32_16x16x32_bf16 v[86:89], v[134:137], v[206:209], v[86:89]
	v_mfma_f32_16x16x32_bf16 v[78:81], v[142:145], v[206:209], v[78:81]
	v_mfma_f32_16x16x32_bf16 v[114:117], v[172:175], v[226:229], v[114:117]
	v_mfma_f32_16x16x32_bf16 v[106:109], v[218:221], v[226:229], v[106:109]
	v_mfma_f32_16x16x32_bf16 v[98:101], v[172:175], v[234:237], v[98:101]
	v_mfma_f32_16x16x32_bf16 v[90:93], v[218:221], v[234:237], v[90:93]
	v_mfma_f32_16x16x32_bf16 v[82:85], v[172:175], v[242:245], v[82:85]
	v_mfma_f32_16x16x32_bf16 v[74:77], v[218:221], v[242:245], v[74:77]
	v_mfma_f32_16x16x32_bf16 v[70:73], v[172:175], v[250:253], v[70:73]
	v_mfma_f32_16x16x32_bf16 v[66:69], v[218:221], v[250:253], v[66:69]
	v_mfma_f32_16x16x32_bf16 v[114:117], v[188:191], v[230:233], v[114:117]
	v_mfma_f32_16x16x32_bf16 v[106:109], v[222:225], v[230:233], v[106:109]
	v_mfma_f32_16x16x32_bf16 v[98:101], v[188:191], v[238:241], v[98:101]
	v_mfma_f32_16x16x32_bf16 v[90:93], v[222:225], v[238:241], v[90:93]
	v_mfma_f32_16x16x32_bf16 v[82:85], v[188:191], v[246:249], v[82:85]
	v_mfma_f32_16x16x32_bf16 v[74:77], v[222:225], v[246:249], v[74:77]
	v_mfma_f32_16x16x32_bf16 v[70:73], v[188:191], v[206:209], v[70:73]
	v_mfma_f32_16x16x32_bf16 v[66:69], v[222:225], v[206:209], v[66:69]
	s_barrier
	s_setprio 0
	s_add_i32 s55, s55, s43
	v_lshl_add_u64 v[154:155], s[10:11], 0, v[148:149]
	s_mov_b32 m0, s55
	ds_read_b128 v[206:209], v171 offset:16384
	ds_read_b128 v[226:229], v171 offset:17408
	ds_read_b128 v[230:233], v171 offset:18432
	ds_read_b128 v[234:237], v171 offset:19456
	ds_read_b128 v[238:241], v171 offset:20480
	ds_read_b128 v[242:245], v171 offset:21504
	ds_read_b128 v[246:249], v171 offset:22528
	ds_read_b128 v[250:253], v171 offset:23552
	global_load_lds_dwordx4 v[154:155], off
	s_add_i32 m0, s55, 0x2000
	s_add_u32 s56, s10, 0x100000
	v_lshl_add_u64 v[176:177], s[10:11], 0, v[146:147]
	s_addc_u32 s57, s11, 0
	s_add_i32 s55, s58, s43
	global_load_lds_dwordx4 v[176:177], off
	v_lshl_add_u64 v[194:195], s[56:57], 0, v[148:149]
	s_mov_b32 m0, s55
	v_lshl_add_u64 v[210:211], s[36:37], 0, v[146:147]
	global_load_lds_dwordx4 v[194:195], off
	v_lshl_add_u64 v[194:195], s[56:57], 0, v[146:147]
	s_add_i32 m0, s55, 0x2000
	s_nop 0
	global_load_lds_dwordx4 v[194:195], off
	v_lshl_add_u64 v[194:195], s[36:37], 0, v[148:149]
	s_mov_b32 m0, s45
	s_nop 0
	global_load_lds_dwordx4 v[194:195], off
	s_mov_b32 m0, s46
	s_nop 0
	global_load_lds_dwordx4 v[210:211], off
	s_waitcnt vmcnt(8)
	s_waitcnt lgkmcnt(0)
	s_setprio 1
	s_barrier
; #define PG8_STAGE(bufoff, gbase, voff) do { _Pragma("unroll") for (int _i = 0; _i < 2; ++_i) \
;         __builtin_amdgcn_global_load_lds((const unsigned*)((const char*)(gbase) + (voff)[_i]), (PG8_LAS unsigned*)(lds + (bufoff) + ldsw + _i * 8192), 16, 0, 0); } while (0)
; #define PG8_LDA(dst, b, h) do { _Pragma("unroll") for (int m = 0; m < 4; ++m) _Pragma("unroll") for (int k = 0; k < 2; ++k) dst[m][k] = *(const PG8_LAS bf16x8*)(lds + PG8_SA(b, h) + aoff + m * 2048 + k * 1024); } while (0)
; #define PG8_LDB(dst, b, h) do { _Pragma("unroll") for (int n = 0; n < 2; ++n) _Pragma("unroll") for (int k = 0; k < 2; ++k) dst[n][k] = *(const PG8_LAS bf16x8*)(lds + PG8_SB(b, h) + boff + n * 2048 + k * 1024); } while (0)
; #define PG8_MMA(ai, bj, At, Bt) do { __builtin_amdgcn_s_setprio(1); _Pragma("unroll") for (int m = 0; m < 4; ++m) _Pragma("unroll") for (int n = 0; n < 2; ++n) _Pragma("unroll") for (int k = 0; k < 2; ++k) \
;         acc[ai][bj][m][n] = __builtin_amdgcn_mfma_f32_16x16x32_bf16(Bt[n][k], At[m][k], acc[ai][bj][m][n], 0, 0, 0); __builtin_amdgcn_s_setprio(0); } while (0)
; #define PG8_WAIT_V(n) asm volatile("s_waitcnt vmcnt(" #n ")" ::: "memory")
; #define PG8_WAIT_L(n) asm volatile("s_waitcnt lgkmcnt(" #n ")" ::: "memory")
; #define PG8_BAR __builtin_amdgcn_s_barrier()
; #define PG8_SCHED __builtin_amdgcn_sched_barrier(0)
; template <class Epi, class Sched, bool ALIGN_EPI, int LMASK = -1, int LMASKB = LMASK>
; __device__ __forceinline__ void gemm_phase(PG8_LAS unsigned char* lds, const Gemm g, const Sched& S, const Epi& E) {
;     ...
;             PG8_WAIT_V(8); PG8_WAIT_L(0); PG8_BAR; PG8_MMA(1, 0, At, B0); PG8_MMA(1, 1, At, B1); PG8_BAR; PG8_SCHED;
;             PG8_LDB(B0, 1, 0); PG8_LDB(B1, 1, 1); PG8_SCHED; PG8_LDA(At, 1, 0); PG8_STAGE(PG8_SA(0, 1), a2 + hstepA, voffA);
;             PG8_WAIT_V(8); PG8_WAIT_L(0); PG8_BAR; PG8_MMA(0, 0, At, B0); PG8_MMA(0, 1, At, B1); PG8_BAR; PG8_SCHED;
	v_mfma_f32_16x16x32_bf16 v[62:65], v[130:133], v[206:209], v[62:65]
	v_mfma_f32_16x16x32_bf16 v[58:61], v[138:141], v[206:209], v[58:61]
	v_mfma_f32_16x16x32_bf16 v[54:57], v[130:133], v[230:233], v[54:57]
	v_mfma_f32_16x16x32_bf16 v[46:49], v[138:141], v[230:233], v[46:49]
	v_mfma_f32_16x16x32_bf16 v[38:41], v[130:133], v[238:241], v[38:41]
	v_mfma_f32_16x16x32_bf16 v[30:33], v[138:141], v[238:241], v[30:33]
	v_mfma_f32_16x16x32_bf16 v[22:25], v[130:133], v[246:249], v[22:25]
	v_mfma_f32_16x16x32_bf16 v[14:17], v[138:141], v[246:249], v[14:17]
	v_mfma_f32_16x16x32_bf16 v[62:65], v[134:137], v[226:229], v[62:65]
	v_mfma_f32_16x16x32_bf16 v[58:61], v[142:145], v[226:229], v[58:61]
	v_mfma_f32_16x16x32_bf16 v[54:57], v[134:137], v[234:237], v[54:57]
	v_mfma_f32_16x16x32_bf16 v[46:49], v[142:145], v[234:237], v[46:49]
	v_mfma_f32_16x16x32_bf16 v[38:41], v[134:137], v[242:245], v[38:41]
	v_mfma_f32_16x16x32_bf16 v[30:33], v[142:145], v[242:245], v[30:33]
	v_mfma_f32_16x16x32_bf16 v[22:25], v[134:137], v[250:253], v[22:25]
	v_mfma_f32_16x16x32_bf16 v[14:17], v[142:145], v[250:253], v[14:17]
	v_mfma_f32_16x16x32_bf16 v[50:53], v[172:175], v[206:209], v[50:53]
	v_mfma_f32_16x16x32_bf16 v[42:45], v[218:221], v[206:209], v[42:45]
	v_mfma_f32_16x16x32_bf16 v[34:37], v[172:175], v[230:233], v[34:37]
	v_mfma_f32_16x16x32_bf16 v[26:29], v[218:221], v[230:233], v[26:29]
	v_mfma_f32_16x16x32_bf16 v[18:21], v[172:175], v[238:241], v[18:21]
	v_mfma_f32_16x16x32_bf16 v[10:13], v[218:221], v[238:241], v[10:13]
	v_mfma_f32_16x16x32_bf16 v[6:9], v[172:175], v[246:249], v[6:9]
	v_mfma_f32_16x16x32_bf16 v[2:5], v[218:221], v[246:249], v[2:5]
	v_mfma_f32_16x16x32_bf16 v[50:53], v[188:191], v[226:229], v[50:53]
	v_mfma_f32_16x16x32_bf16 v[42:45], v[222:225], v[226:229], v[42:45]
	v_mfma_f32_16x16x32_bf16 v[34:37], v[188:191], v[234:237], v[34:37]
	v_mfma_f32_16x16x32_bf16 v[26:29], v[222:225], v[234:237], v[26:29]
	v_mfma_f32_16x16x32_bf16 v[18:21], v[188:191], v[242:245], v[18:21]
	v_mfma_f32_16x16x32_bf16 v[10:13], v[222:225], v[242:245], v[10:13]
	v_mfma_f32_16x16x32_bf16 v[6:9], v[188:191], v[250:253], v[6:9]
	v_mfma_f32_16x16x32_bf16 v[2:5], v[222:225], v[250:253], v[2:5]
	s_barrier
	s_setprio 0
	s_add_i32 s55, 0, 0x18000
	s_add_i32 s56, 0, 0x1c000
	v_add_u32_e32 v142, s55, v161
	v_add_u32_e32 v156, s56, v161
	ds_read_b128 v[130:133], v142
	ds_read_b128 v[134:137], v142 offset:1024
	ds_read_b128 v[138:141], v142 offset:2048
	ds_read_b128 v[142:145], v142 offset:3072
	ds_read_b128 v[172:175], v156
	ds_read_b128 v[188:191], v156 offset:1024
	ds_read_b128 v[206:209], v156 offset:2048
	ds_read_b128 v[218:221], v156 offset:3072
	s_add_u32 s36, s36, 0x100000
	s_addc_u32 s37, s37, 0
	s_mov_b32 m0, s47
	v_lshl_add_u64 v[212:213], s[36:37], 0, v[148:149]
	ds_read_b128 v[222:225], v171 offset:32768
	ds_read_b128 v[226:229], v171 offset:33792
	ds_read_b128 v[230:233], v171 offset:34816
	ds_read_b128 v[234:237], v171 offset:35840
	ds_read_b128 v[238:241], v171 offset:36864
	ds_read_b128 v[242:245], v171 offset:37888
	ds_read_b128 v[246:249], v171 offset:38912
	ds_read_b128 v[250:253], v171 offset:39936
	global_load_lds_dwordx4 v[212:213], off
	v_lshl_add_u64 v[212:213], s[36:37], 0, v[146:147]
	s_mov_b32 m0, s48
	s_nop 0
	global_load_lds_dwordx4 v[212:213], off
	s_waitcnt vmcnt(8)
	s_waitcnt lgkmcnt(0)
	s_setprio 1
	s_barrier
	v_mfma_f32_16x16x32_bf16 v[126:129], v[130:133], v[222:225], v[126:129]
	v_mfma_f32_16x16x32_bf16 v[122:125], v[138:141], v[222:225], v[122:125]
	v_mfma_f32_16x16x32_bf16 v[118:121], v[130:133], v[230:233], v[118:121]
	v_mfma_f32_16x16x32_bf16 v[110:113], v[138:141], v[230:233], v[110:113]
	v_mfma_f32_16x16x32_bf16 v[102:105], v[130:133], v[238:241], v[102:105]
	v_mfma_f32_16x16x32_bf16 v[94:97], v[138:141], v[238:241], v[94:97]
	v_mfma_f32_16x16x32_bf16 v[86:89], v[130:133], v[246:249], v[86:89]
	v_mfma_f32_16x16x32_bf16 v[78:81], v[138:141], v[246:249], v[78:81]
	v_mfma_f32_16x16x32_bf16 v[126:129], v[134:137], v[226:229], v[126:129]
	v_mfma_f32_16x16x32_bf16 v[122:125], v[142:145], v[226:229], v[122:125]
	v_mfma_f32_16x16x32_bf16 v[118:121], v[134:137], v[234:237], v[118:121]
	v_mfma_f32_16x16x32_bf16 v[110:113], v[142:145], v[234:237], v[110:113]
	v_mfma_f32_16x16x32_bf16 v[102:105], v[134:137], v[242:245], v[102:105]
	v_mfma_f32_16x16x32_bf16 v[94:97], v[142:145], v[242:245], v[94:97]
	v_mfma_f32_16x16x32_bf16 v[86:89], v[134:137], v[250:253], v[86:89]
	v_mfma_f32_16x16x32_bf16 v[78:81], v[142:145], v[250:253], v[78:81]
	v_mfma_f32_16x16x32_bf16 v[114:117], v[172:175], v[222:225], v[114:117]
	v_mfma_f32_16x16x32_bf16 v[106:109], v[206:209], v[222:225], v[106:109]
	v_mfma_f32_16x16x32_bf16 v[98:101], v[172:175], v[230:233], v[98:101]
	v_mfma_f32_16x16x32_bf16 v[90:93], v[206:209], v[230:233], v[90:93]
	v_mfma_f32_16x16x32_bf16 v[82:85], v[172:175], v[238:241], v[82:85]
	v_mfma_f32_16x16x32_bf16 v[74:77], v[206:209], v[238:241], v[74:77]
	v_mfma_f32_16x16x32_bf16 v[70:73], v[172:175], v[246:249], v[70:73]
	v_mfma_f32_16x16x32_bf16 v[66:69], v[206:209], v[246:249], v[66:69]
	v_mfma_f32_16x16x32_bf16 v[114:117], v[188:191], v[226:229], v[114:117]
	v_mfma_f32_16x16x32_bf16 v[106:109], v[218:221], v[226:229], v[106:109]
	v_mfma_f32_16x16x32_bf16 v[98:101], v[188:191], v[234:237], v[98:101]
	v_mfma_f32_16x16x32_bf16 v[90:93], v[218:221], v[234:237], v[90:93]
	v_mfma_f32_16x16x32_bf16 v[82:85], v[188:191], v[242:245], v[82:85]
	v_mfma_f32_16x16x32_bf16 v[74:77], v[218:221], v[242:245], v[74:77]
	v_mfma_f32_16x16x32_bf16 v[70:73], v[188:191], v[250:253], v[70:73]
	v_mfma_f32_16x16x32_bf16 v[66:69], v[218:221], v[250:253], v[66:69]
	s_barrier
; #define PG8_STAGE(bufoff, gbase, voff) do { _Pragma("unroll") for (int _i = 0; _i < 2; ++_i) \
;         __builtin_amdgcn_global_load_lds((const unsigned*)((const char*)(gbase) + (voff)[_i]), (PG8_LAS unsigned*)(lds + (bufoff) + ldsw + _i * 8192), 16, 0, 0); } while (0)
; #define PG8_LDA(dst, b, h) do { _Pragma("unroll") for (int m = 0; m < 4; ++m) _Pragma("unroll") for (int k = 0; k < 2; ++k) dst[m][k] = *(const PG8_LAS bf16x8*)(lds + PG8_SA(b, h) + aoff + m * 2048 + k * 1024); } while (0)
; #define PG8_MMA(ai, bj, At, Bt) do { __builtin_amdgcn_s_setprio(1); _Pragma("unroll") for (int m = 0; m < 4; ++m) _Pragma("unroll") for (int n = 0; n < 2; ++n) _Pragma("unroll") for (int k = 0; k < 2; ++k) \
;         acc[ai][bj][m][n] = __builtin_amdgcn_mfma_f32_16x16x32_bf16(Bt[n][k], At[m][k], acc[ai][bj][m][n], 0, 0, 0); __builtin_amdgcn_s_setprio(0); } while (0)
; #define PG8_WAIT_V(n) asm volatile("s_waitcnt vmcnt(" #n ")" ::: "memory")
; #define PG8_WAIT_L(n) asm volatile("s_waitcnt lgkmcnt(" #n ")" ::: "memory")
; #define PG8_BAR __builtin_amdgcn_s_barrier()
; #define PG8_SCHED __builtin_amdgcn_sched_barrier(0)
; template <class Epi, class Sched, bool ALIGN_EPI, int LMASK = -1, int LMASKB = LMASK>
; __device__ __forceinline__ void gemm_phase(PG8_LAS unsigned char* lds, const Gemm g, const Sched& S, const Epi& E) {
;     ...
;             PG8_LDA(At, 1, 1); PG8_STAGE(PG8_SB(1, 0), b3, voffB); PG8_STAGE(PG8_SB(1, 1), b3 + hstepB, voffB); PG8_STAGE(PG8_SA(1, 0), a3, voffA);
;             PG8_WAIT_V(8); PG8_WAIT_L(0); PG8_BAR; PG8_MMA(1, 0, At, B0); PG8_MMA(1, 1, At, B1); PG8_BAR; PG8_SCHED;
;         }
;         if constexpr (ALIGN_EPI) { if (wr == 0) PG8_BAR; }
;         E(acc, cur, wr, wc, fr, fq);
;         if (!has_next) break;
	s_setprio 0
	s_add_i32 s36, s55, s43
	v_lshl_add_u64 v[154:155], v[154:155], 0, s[80:81]
	s_mov_b32 m0, s36
	ds_read_b128 v[222:225], v171 offset:49152
	ds_read_b128 v[226:229], v171 offset:50176
	ds_read_b128 v[230:233], v171 offset:51200
	ds_read_b128 v[234:237], v171 offset:52224
	ds_read_b128 v[238:241], v171 offset:53248
	ds_read_b128 v[242:245], v171 offset:54272
	ds_read_b128 v[246:249], v171 offset:55296
	ds_read_b128 v[250:253], v171 offset:56320
	global_load_lds_dwordx4 v[154:155], off
	s_add_i32 m0, s36, 0x2000
	s_add_u32 s10, s10, 0x100800
	v_lshl_add_u64 v[154:155], v[176:177], 0, s[80:81]
	s_addc_u32 s11, s11, 0
	s_add_i32 s36, s56, s43
	global_load_lds_dwordx4 v[154:155], off
	v_lshl_add_u64 v[154:155], s[10:11], 0, v[148:149]
	s_mov_b32 m0, s36
	s_nop 0
	global_load_lds_dwordx4 v[154:155], off
	v_lshl_add_u64 v[154:155], s[10:11], 0, v[146:147]
	s_add_i32 m0, s36, 0x2000
	s_nop 0
	global_load_lds_dwordx4 v[154:155], off
	v_lshl_add_u64 v[154:155], v[194:195], 0, s[80:81]
	s_mov_b32 m0, s49
	s_nop 0
	global_load_lds_dwordx4 v[154:155], off
	v_lshl_add_u64 v[154:155], v[210:211], 0, s[80:81]
	s_mov_b32 m0, s50
	s_nop 0
	global_load_lds_dwordx4 v[154:155], off
	s_waitcnt vmcnt(8)
	s_waitcnt lgkmcnt(0)
	s_setprio 1
	s_barrier
	v_mfma_f32_16x16x32_bf16 v[62:65], v[130:133], v[222:225], v[62:65]
	v_mfma_f32_16x16x32_bf16 v[58:61], v[138:141], v[222:225], v[58:61]
	v_mfma_f32_16x16x32_bf16 v[54:57], v[130:133], v[230:233], v[54:57]
	v_mfma_f32_16x16x32_bf16 v[46:49], v[138:141], v[230:233], v[46:49]
	v_mfma_f32_16x16x32_bf16 v[38:41], v[130:133], v[238:241], v[38:41]
	v_mfma_f32_16x16x32_bf16 v[30:33], v[138:141], v[238:241], v[30:33]
	v_mfma_f32_16x16x32_bf16 v[22:25], v[130:133], v[246:249], v[22:25]
	v_mfma_f32_16x16x32_bf16 v[14:17], v[138:141], v[246:249], v[14:17]
	v_mfma_f32_16x16x32_bf16 v[62:65], v[134:137], v[226:229], v[62:65]
	v_mfma_f32_16x16x32_bf16 v[58:61], v[142:145], v[226:229], v[58:61]
	v_mfma_f32_16x16x32_bf16 v[54:57], v[134:137], v[234:237], v[54:57]
	v_mfma_f32_16x16x32_bf16 v[46:49], v[142:145], v[234:237], v[46:49]
	v_mfma_f32_16x16x32_bf16 v[38:41], v[134:137], v[242:245], v[38:41]
	v_mfma_f32_16x16x32_bf16 v[30:33], v[142:145], v[242:245], v[30:33]
	v_mfma_f32_16x16x32_bf16 v[22:25], v[134:137], v[250:253], v[22:25]
	v_mfma_f32_16x16x32_bf16 v[14:17], v[142:145], v[250:253], v[14:17]
	v_mfma_f32_16x16x32_bf16 v[50:53], v[172:175], v[222:225], v[50:53]
	v_mfma_f32_16x16x32_bf16 v[42:45], v[206:209], v[222:225], v[42:45]
	v_mfma_f32_16x16x32_bf16 v[34:37], v[172:175], v[230:233], v[34:37]
	v_mfma_f32_16x16x32_bf16 v[26:29], v[206:209], v[230:233], v[26:29]
	v_mfma_f32_16x16x32_bf16 v[18:21], v[172:175], v[238:241], v[18:21]
	v_mfma_f32_16x16x32_bf16 v[10:13], v[206:209], v[238:241], v[10:13]
	v_mfma_f32_16x16x32_bf16 v[6:9], v[172:175], v[246:249], v[6:9]
	v_mfma_f32_16x16x32_bf16 v[2:5], v[206:209], v[246:249], v[2:5]
	v_mfma_f32_16x16x32_bf16 v[50:53], v[188:191], v[226:229], v[50:53]
	v_mfma_f32_16x16x32_bf16 v[42:45], v[218:221], v[226:229], v[42:45]
	v_mfma_f32_16x16x32_bf16 v[34:37], v[188:191], v[234:237], v[34:37]
	v_mfma_f32_16x16x32_bf16 v[26:29], v[218:221], v[234:237], v[26:29]
	v_mfma_f32_16x16x32_bf16 v[18:21], v[188:191], v[242:245], v[18:21]
	v_mfma_f32_16x16x32_bf16 v[10:13], v[218:221], v[242:245], v[10:13]
	v_mfma_f32_16x16x32_bf16 v[6:9], v[188:191], v[250:253], v[6:9]
	v_mfma_f32_16x16x32_bf16 v[2:5], v[218:221], v[250:253], v[2:5]
	s_barrier
	s_setprio 0
	s_add_i32 s54, s54, 2
	s_add_u32 s8, s8, 0x1000
	s_addc_u32 s9, s9, 0
	s_add_u32 s27, s27, 0x1000
	s_addc_u32 s29, s29, 0
	s_cmp_gt_u32 s54, 61
	s_cbranch_scc0 .LBB0_284
	s_and_b64 vcc, exec, s[22:23]
	s_cbranch_vccz .LBB0_287
	s_barrier

; #define PG8_STAGE(bufoff, gbase, voff) do { _Pragma("unroll") for (int _i = 0; _i < 2; ++_i) \
;         __builtin_amdgcn_global_load_lds((const unsigned*)((const char*)(gbase) + (voff)[_i]), (PG8_LAS unsigned*)(lds + (bufoff) + ldsw + _i * 8192), 16, 0, 0); } while (0)
; #define PG8_LDA(dst, b, h) do { _Pragma("unroll") for (int m = 0; m < 4; ++m) _Pragma("unroll") for (int k = 0; k < 2; ++k) dst[m][k] = *(const PG8_LAS bf16x8*)(lds + PG8_SA(b, h) + aoff + m * 2048 + k * 1024); } while (0)
; #define PG8_LDB(dst, b, h) do { _Pragma("unroll") for (int n = 0; n < 2; ++n) _Pragma("unroll") for (int k = 0; k < 2; ++k) dst[n][k] = *(const PG8_LAS bf16x8*)(lds + PG8_SB(b, h) + boff + n * 2048 + k * 1024); } while (0)
; #define PG8_MMA(ai, bj, At, Bt) do { __builtin_amdgcn_s_setprio(1); _Pragma("unroll") for (int m = 0; m < 4; ++m) _Pragma("unroll") for (int n = 0; n < 2; ++n) _Pragma("unroll") for (int k = 0; k < 2; ++k) \
;         acc[ai][bj][m][n] = __builtin_amdgcn_mfma_f32_16x16x32_bf16(Bt[n][k], At[m][k], acc[ai][bj][m][n], 0, 0, 0); __builtin_amdgcn_s_setprio(0); } while (0)
; #define PG8_WAIT_V(n) asm volatile("s_waitcnt vmcnt(" #n ")" ::: "memory")
; #define PG8_WAIT_L(n) asm volatile("s_waitcnt lgkmcnt(" #n ")" ::: "memory")
; #define PG8_BAR __builtin_amdgcn_s_barrier()
; #define PG8_SCHED __builtin_amdgcn_sched_barrier(0)
; template <class Epi, class Sched, bool ALIGN_EPI, int LMASK = -1, int LMASKB = LMASK>
; __device__ __forceinline__ void gemm_phase(PG8_LAS unsigned char* lds, const Gemm g, const Sched& S, const Epi& E) {
;     ...
;             const bool last = (t == nt - 2);
;             const char* a1 = cA + (size_t)(t + 1) * kstepA;
;             const char* a2 = last ? nA : cA + (size_t)(t + 2) * kstepA; const char* b2 = last ? nB : cB + (size_t)(t + 2) * kstepB;
;             const char* a3 = a2 + kstepA; const char* b3 = b2 + kstepB;
;             PG8_LDB(B0, 0, 0); PG8_LDB(B1, 0, 1); PG8_SCHED; PG8_LDA(At, 0, 0); PG8_STAGE(PG8_SA(1, 1), a1 + hstepA, voffA);
;             PG8_WAIT_V(8); PG8_WAIT_L(0); PG8_BAR; PG8_MMA(0, 0, At, B0); PG8_MMA(0, 1, At, B1); PG8_BAR; PG8_SCHED;
;             PG8_LDA(At, 0, 1); PG8_STAGE(PG8_SB(0, 0), b2, voffB); PG8_STAGE(PG8_SB(0, 1), b2 + hstepB, voffB); PG8_STAGE(PG8_SA(0, 0), a2, voffA);
.LBB0_580:
	s_add_u32 s30, s28, 0xfff00800
	s_addc_u32 s31, s29, -1
	s_add_i32 s51, 0, 0x10000
	s_cmp_eq_u32 s50, 60
	s_cselect_b32 s35, s19, s31
	s_cselect_b32 s34, s25, s30
	v_add_u32_e32 v146, s51, v149
	s_cselect_b32 s31, s17, s49
	s_cselect_b32 s30, s47, s48
	s_add_i32 s54, 0, 0x14000
	ds_read_b128 v[130:133], v146
	ds_read_b128 v[142:145], v146 offset:1024
	ds_read_b128 v[152:155], v146 offset:2048
	ds_read_b128 v[156:159], v146 offset:3072
	v_add_u32_e32 v146, s54, v149
	ds_read_b128 v[160:163], v146
	ds_read_b128 v[164:167], v146 offset:1024
	ds_read_b128 v[168:171], v146 offset:2048
	ds_read_b128 v[172:175], v146 offset:3072
	v_lshl_add_u64 v[146:147], s[28:29], 0, v[138:139]
	s_add_i32 m0, s27, 0xc000
	ds_read_b128 v[188:191], v151
	ds_read_b128 v[206:209], v151 offset:1024
	ds_read_b128 v[218:221], v151 offset:2048
	ds_read_b128 v[222:225], v151 offset:3072
	ds_read_b128 v[226:229], v151 offset:4096
	ds_read_b128 v[230:233], v151 offset:5120
	ds_read_b128 v[234:237], v151 offset:6144
	ds_read_b128 v[238:241], v151 offset:7168
	global_load_lds_dwordx4 v[146:147], off
	v_lshl_add_u64 v[146:147], s[28:29], 0, v[140:141]
	s_add_i32 m0, s27, 0xe000
	s_nop 0
	global_load_lds_dwordx4 v[146:147], off
	s_waitcnt vmcnt(8)
	s_waitcnt lgkmcnt(0)
	s_setprio 1
	s_barrier
	v_mfma_f32_16x16x32_bf16 v[126:129], v[130:133], v[188:191], v[126:129]
	v_mfma_f32_16x16x32_bf16 v[122:125], v[152:155], v[188:191], v[122:125]
	v_mfma_f32_16x16x32_bf16 v[110:113], v[130:133], v[218:221], v[110:113]
	v_mfma_f32_16x16x32_bf16 v[106:109], v[152:155], v[218:221], v[106:109]
	v_mfma_f32_16x16x32_bf16 v[94:97], v[130:133], v[226:229], v[94:97]
	v_mfma_f32_16x16x32_bf16 v[90:93], v[152:155], v[226:229], v[90:93]
	v_mfma_f32_16x16x32_bf16 v[78:81], v[130:133], v[234:237], v[78:81]
	v_mfma_f32_16x16x32_bf16 v[74:77], v[152:155], v[234:237], v[74:77]
	v_mfma_f32_16x16x32_bf16 v[126:129], v[142:145], v[206:209], v[126:129]
	v_mfma_f32_16x16x32_bf16 v[122:125], v[156:159], v[206:209], v[122:125]
	v_mfma_f32_16x16x32_bf16 v[110:113], v[142:145], v[222:225], v[110:113]
	v_mfma_f32_16x16x32_bf16 v[106:109], v[156:159], v[222:225], v[106:109]
	v_mfma_f32_16x16x32_bf16 v[94:97], v[142:145], v[230:233], v[94:97]
	v_mfma_f32_16x16x32_bf16 v[90:93], v[156:159], v[230:233], v[90:93]
	v_mfma_f32_16x16x32_bf16 v[78:81], v[142:145], v[238:241], v[78:81]
	v_mfma_f32_16x16x32_bf16 v[74:77], v[156:159], v[238:241], v[74:77]
	v_mfma_f32_16x16x32_bf16 v[118:121], v[160:163], v[188:191], v[118:121]
	v_mfma_f32_16x16x32_bf16 v[114:117], v[168:171], v[188:191], v[114:117]
	v_mfma_f32_16x16x32_bf16 v[102:105], v[160:163], v[218:221], v[102:105]
	v_mfma_f32_16x16x32_bf16 v[98:101], v[168:171], v[218:221], v[98:101]
	v_mfma_f32_16x16x32_bf16 v[86:89], v[160:163], v[226:229], v[86:89]
	v_mfma_f32_16x16x32_bf16 v[82:85], v[168:171], v[226:229], v[82:85]
	v_mfma_f32_16x16x32_bf16 v[70:73], v[160:163], v[234:237], v[70:73]
	v_mfma_f32_16x16x32_bf16 v[66:69], v[168:171], v[234:237], v[66:69]
	v_mfma_f32_16x16x32_bf16 v[118:121], v[164:167], v[206:209], v[118:121]
	v_mfma_f32_16x16x32_bf16 v[114:117], v[172:175], v[206:209], v[114:117]
	v_mfma_f32_16x16x32_bf16 v[102:105], v[164:167], v[222:225], v[102:105]
	v_mfma_f32_16x16x32_bf16 v[98:101], v[172:175], v[222:225], v[98:101]
	v_mfma_f32_16x16x32_bf16 v[86:89], v[164:167], v[230:233], v[86:89]
	v_mfma_f32_16x16x32_bf16 v[82:85], v[172:175], v[230:233], v[82:85]
	v_mfma_f32_16x16x32_bf16 v[70:73], v[164:167], v[238:241], v[70:73]
	v_mfma_f32_16x16x32_bf16 v[66:69], v[172:175], v[238:241], v[66:69]
	s_barrier
	s_setprio 0
	s_add_i32 s51, s51, s38
	v_lshl_add_u64 v[146:147], s[30:31], 0, v[134:135]
	s_mov_b32 m0, s51
	ds_read_b128 v[188:191], v151 offset:16384
	ds_read_b128 v[206:209], v151 offset:17408
	ds_read_b128 v[218:221], v151 offset:18432
	ds_read_b128 v[222:225], v151 offset:19456
	ds_read_b128 v[226:229], v151 offset:20480
	ds_read_b128 v[230:233], v151 offset:21504
	ds_read_b128 v[234:237], v151 offset:22528
	ds_read_b128 v[238:241], v151 offset:23552
	global_load_lds_dwordx4 v[146:147], off
	s_add_i32 m0, s51, 0x2000
	s_add_u32 s52, s30, 0x100000
	v_lshl_add_u64 v[176:177], s[30:31], 0, v[136:137]
	s_addc_u32 s53, s31, 0
	s_add_i32 s51, s54, s38
	global_load_lds_dwordx4 v[176:177], off
	v_lshl_add_u64 v[194:195], s[52:53], 0, v[134:135]
	s_mov_b32 m0, s51
	v_lshl_add_u64 v[210:211], s[34:35], 0, v[136:137]
	global_load_lds_dwordx4 v[194:195], off
	v_lshl_add_u64 v[194:195], s[52:53], 0, v[136:137]
	s_add_i32 m0, s51, 0x2000
	s_nop 0
	global_load_lds_dwordx4 v[194:195], off
	v_lshl_add_u64 v[194:195], s[34:35], 0, v[134:135]
	s_mov_b32 m0, s27
	s_nop 0
	global_load_lds_dwordx4 v[194:195], off
	s_mov_b32 m0, s39
	s_nop 0
	global_load_lds_dwordx4 v[210:211], off
	s_waitcnt vmcnt(8)
	s_waitcnt lgkmcnt(0)
	s_setprio 1
	s_barrier
; #define PG8_STAGE(bufoff, gbase, voff) do { _Pragma("unroll") for (int _i = 0; _i < 2; ++_i) \
;         __builtin_amdgcn_global_load_lds((const unsigned*)((const char*)(gbase) + (voff)[_i]), (PG8_LAS unsigned*)(lds + (bufoff) + ldsw + _i * 8192), 16, 0, 0); } while (0)
; #define PG8_LDA(dst, b, h) do { _Pragma("unroll") for (int m = 0; m < 4; ++m) _Pragma("unroll") for (int k = 0; k < 2; ++k) dst[m][k] = *(const PG8_LAS bf16x8*)(lds + PG8_SA(b, h) + aoff + m * 2048 + k * 1024); } while (0)
; #define PG8_LDB(dst, b, h) do { _Pragma("unroll") for (int n = 0; n < 2; ++n) _Pragma("unroll") for (int k = 0; k < 2; ++k) dst[n][k] = *(const PG8_LAS bf16x8*)(lds + PG8_SB(b, h) + boff + n * 2048 + k * 1024); } while (0)
; #define PG8_MMA(ai, bj, At, Bt) do { __builtin_amdgcn_s_setprio(1); _Pragma("unroll") for (int m = 0; m < 4; ++m) _Pragma("unroll") for (int n = 0; n < 2; ++n) _Pragma("unroll") for (int k = 0; k < 2; ++k) \
;         acc[ai][bj][m][n] = __builtin_amdgcn_mfma_f32_16x16x32_bf16(Bt[n][k], At[m][k], acc[ai][bj][m][n], 0, 0, 0); __builtin_amdgcn_s_setprio(0); } while (0)
; #define PG8_WAIT_V(n) asm volatile("s_waitcnt vmcnt(" #n ")" ::: "memory")
; #define PG8_WAIT_L(n) asm volatile("s_waitcnt lgkmcnt(" #n ")" ::: "memory")
; #define PG8_BAR __builtin_amdgcn_s_barrier()
; #define PG8_SCHED __builtin_amdgcn_sched_barrier(0)
; template <class Epi, class Sched, bool ALIGN_EPI, int LMASK = -1, int LMASKB = LMASK>
; __device__ __forceinline__ void gemm_phase(PG8_LAS unsigned char* lds, const Gemm g, const Sched& S, const Epi& E) {
;     ...
;             PG8_WAIT_V(8); PG8_WAIT_L(0); PG8_BAR; PG8_MMA(1, 0, At, B0); PG8_MMA(1, 1, At, B1); PG8_BAR; PG8_SCHED;
;             PG8_LDB(B0, 1, 0); PG8_LDB(B1, 1, 1); PG8_SCHED; PG8_LDA(At, 1, 0); PG8_STAGE(PG8_SA(0, 1), a2 + hstepA, voffA);
;             PG8_WAIT_V(8); PG8_WAIT_L(0); PG8_BAR; PG8_MMA(0, 0, At, B0); PG8_MMA(0, 1, At, B1); PG8_BAR; PG8_SCHED;
	v_mfma_f32_16x16x32_bf16 v[62:65], v[130:133], v[188:191], v[62:65]
	v_mfma_f32_16x16x32_bf16 v[58:61], v[152:155], v[188:191], v[58:61]
	v_mfma_f32_16x16x32_bf16 v[46:49], v[130:133], v[218:221], v[46:49]
	v_mfma_f32_16x16x32_bf16 v[42:45], v[152:155], v[218:221], v[42:45]
	v_mfma_f32_16x16x32_bf16 v[30:33], v[130:133], v[226:229], v[30:33]
	v_mfma_f32_16x16x32_bf16 v[26:29], v[152:155], v[226:229], v[26:29]
	v_mfma_f32_16x16x32_bf16 v[14:17], v[130:133], v[234:237], v[14:17]
	v_mfma_f32_16x16x32_bf16 v[10:13], v[152:155], v[234:237], v[10:13]
	v_mfma_f32_16x16x32_bf16 v[62:65], v[142:145], v[206:209], v[62:65]
	v_mfma_f32_16x16x32_bf16 v[58:61], v[156:159], v[206:209], v[58:61]
	v_mfma_f32_16x16x32_bf16 v[46:49], v[142:145], v[222:225], v[46:49]
	v_mfma_f32_16x16x32_bf16 v[42:45], v[156:159], v[222:225], v[42:45]
	v_mfma_f32_16x16x32_bf16 v[30:33], v[142:145], v[230:233], v[30:33]
	v_mfma_f32_16x16x32_bf16 v[26:29], v[156:159], v[230:233], v[26:29]
	v_mfma_f32_16x16x32_bf16 v[14:17], v[142:145], v[238:241], v[14:17]
	v_mfma_f32_16x16x32_bf16 v[10:13], v[156:159], v[238:241], v[10:13]
	v_mfma_f32_16x16x32_bf16 v[54:57], v[160:163], v[188:191], v[54:57]
	v_mfma_f32_16x16x32_bf16 v[50:53], v[168:171], v[188:191], v[50:53]
	v_mfma_f32_16x16x32_bf16 v[38:41], v[160:163], v[218:221], v[38:41]
	v_mfma_f32_16x16x32_bf16 v[34:37], v[168:171], v[218:221], v[34:37]
	v_mfma_f32_16x16x32_bf16 v[22:25], v[160:163], v[226:229], v[22:25]
	v_mfma_f32_16x16x32_bf16 v[18:21], v[168:171], v[226:229], v[18:21]
	v_mfma_f32_16x16x32_bf16 v[6:9], v[160:163], v[234:237], v[6:9]
	v_mfma_f32_16x16x32_bf16 v[2:5], v[168:171], v[234:237], v[2:5]
	v_mfma_f32_16x16x32_bf16 v[54:57], v[164:167], v[206:209], v[54:57]
	v_mfma_f32_16x16x32_bf16 v[50:53], v[172:175], v[206:209], v[50:53]
	v_mfma_f32_16x16x32_bf16 v[38:41], v[164:167], v[222:225], v[38:41]
	v_mfma_f32_16x16x32_bf16 v[34:37], v[172:175], v[222:225], v[34:37]
	v_mfma_f32_16x16x32_bf16 v[22:25], v[164:167], v[230:233], v[22:25]
	v_mfma_f32_16x16x32_bf16 v[18:21], v[172:175], v[230:233], v[18:21]
	v_mfma_f32_16x16x32_bf16 v[6:9], v[164:167], v[238:241], v[6:9]
	v_mfma_f32_16x16x32_bf16 v[2:5], v[172:175], v[238:241], v[2:5]
	s_barrier
	s_setprio 0
	s_add_i32 s51, 0, 0x18000
	s_add_i32 s52, 0, 0x1c000
	v_add_u32_e32 v156, s51, v149
	v_add_u32_e32 v172, s52, v149
	ds_read_b128 v[130:133], v156
	ds_read_b128 v[142:145], v156 offset:1024
	ds_read_b128 v[152:155], v156 offset:2048
	ds_read_b128 v[156:159], v156 offset:3072
	ds_read_b128 v[160:163], v172
	ds_read_b128 v[164:167], v172 offset:1024
	ds_read_b128 v[168:171], v172 offset:2048
	ds_read_b128 v[172:175], v172 offset:3072
	s_add_u32 s34, s34, 0x100000
	s_addc_u32 s35, s35, 0
	s_mov_b32 m0, s40
	v_lshl_add_u64 v[212:213], s[34:35], 0, v[134:135]
	ds_read_b128 v[188:191], v151 offset:32768
	ds_read_b128 v[206:209], v151 offset:33792
	ds_read_b128 v[218:221], v151 offset:34816
	ds_read_b128 v[222:225], v151 offset:35840
	ds_read_b128 v[226:229], v151 offset:36864
	ds_read_b128 v[230:233], v151 offset:37888
	ds_read_b128 v[234:237], v151 offset:38912
	ds_read_b128 v[238:241], v151 offset:39936
	global_load_lds_dwordx4 v[212:213], off
	v_lshl_add_u64 v[212:213], s[34:35], 0, v[136:137]
	s_mov_b32 m0, s41
	s_nop 0
	global_load_lds_dwordx4 v[212:213], off
	s_waitcnt vmcnt(8)
	s_waitcnt lgkmcnt(0)
	s_setprio 1
	s_barrier
	v_mfma_f32_16x16x32_bf16 v[126:129], v[130:133], v[188:191], v[126:129]
	v_mfma_f32_16x16x32_bf16 v[122:125], v[152:155], v[188:191], v[122:125]
	v_mfma_f32_16x16x32_bf16 v[110:113], v[130:133], v[218:221], v[110:113]
	v_mfma_f32_16x16x32_bf16 v[106:109], v[152:155], v[218:221], v[106:109]
	v_mfma_f32_16x16x32_bf16 v[94:97], v[130:133], v[226:229], v[94:97]
	v_mfma_f32_16x16x32_bf16 v[90:93], v[152:155], v[226:229], v[90:93]
	v_mfma_f32_16x16x32_bf16 v[78:81], v[130:133], v[234:237], v[78:81]
	v_mfma_f32_16x16x32_bf16 v[74:77], v[152:155], v[234:237], v[74:77]
	v_mfma_f32_16x16x32_bf16 v[126:129], v[142:145], v[206:209], v[126:129]
	v_mfma_f32_16x16x32_bf16 v[122:125], v[156:159], v[206:209], v[122:125]
	v_mfma_f32_16x16x32_bf16 v[110:113], v[142:145], v[222:225], v[110:113]
	v_mfma_f32_16x16x32_bf16 v[106:109], v[156:159], v[222:225], v[106:109]
	v_mfma_f32_16x16x32_bf16 v[94:97], v[142:145], v[230:233], v[94:97]
	v_mfma_f32_16x16x32_bf16 v[90:93], v[156:159], v[230:233], v[90:93]
	v_mfma_f32_16x16x32_bf16 v[78:81], v[142:145], v[238:241], v[78:81]
	v_mfma_f32_16x16x32_bf16 v[74:77], v[156:159], v[238:241], v[74:77]
	v_mfma_f32_16x16x32_bf16 v[118:121], v[160:163], v[188:191], v[118:121]
	v_mfma_f32_16x16x32_bf16 v[114:117], v[168:171], v[188:191], v[114:117]
	v_mfma_f32_16x16x32_bf16 v[102:105], v[160:163], v[218:221], v[102:105]
	v_mfma_f32_16x16x32_bf16 v[98:101], v[168:171], v[218:221], v[98:101]
	v_mfma_f32_16x16x32_bf16 v[86:89], v[160:163], v[226:229], v[86:89]
	v_mfma_f32_16x16x32_bf16 v[82:85], v[168:171], v[226:229], v[82:85]
	v_mfma_f32_16x16x32_bf16 v[70:73], v[160:163], v[234:237], v[70:73]
	v_mfma_f32_16x16x32_bf16 v[66:69], v[168:171], v[234:237], v[66:69]
	v_mfma_f32_16x16x32_bf16 v[118:121], v[164:167], v[206:209], v[118:121]
	v_mfma_f32_16x16x32_bf16 v[114:117], v[172:175], v[206:209], v[114:117]
	v_mfma_f32_16x16x32_bf16 v[102:105], v[164:167], v[222:225], v[102:105]
	v_mfma_f32_16x16x32_bf16 v[98:101], v[172:175], v[222:225], v[98:101]
	v_mfma_f32_16x16x32_bf16 v[86:89], v[164:167], v[230:233], v[86:89]
	v_mfma_f32_16x16x32_bf16 v[82:85], v[172:175], v[230:233], v[82:85]
	v_mfma_f32_16x16x32_bf16 v[70:73], v[164:167], v[238:241], v[70:73]
	v_mfma_f32_16x16x32_bf16 v[66:69], v[172:175], v[238:241], v[66:69]
	s_barrier
; #define PG8_STAGE(bufoff, gbase, voff) do { _Pragma("unroll") for (int _i = 0; _i < 2; ++_i) \
;         __builtin_amdgcn_global_load_lds((const unsigned*)((const char*)(gbase) + (voff)[_i]), (PG8_LAS unsigned*)(lds + (bufoff) + ldsw + _i * 8192), 16, 0, 0); } while (0)
; #define PG8_LDA(dst, b, h) do { _Pragma("unroll") for (int m = 0; m < 4; ++m) _Pragma("unroll") for (int k = 0; k < 2; ++k) dst[m][k] = *(const PG8_LAS bf16x8*)(lds + PG8_SA(b, h) + aoff + m * 2048 + k * 1024); } while (0)
; #define PG8_MMA(ai, bj, At, Bt) do { __builtin_amdgcn_s_setprio(1); _Pragma("unroll") for (int m = 0; m < 4; ++m) _Pragma("unroll") for (int n = 0; n < 2; ++n) _Pragma("unroll") for (int k = 0; k < 2; ++k) \
;         acc[ai][bj][m][n] = __builtin_amdgcn_mfma_f32_16x16x32_bf16(Bt[n][k], At[m][k], acc[ai][bj][m][n], 0, 0, 0); __builtin_amdgcn_s_setprio(0); } while (0)
; #define PG8_WAIT_V(n) asm volatile("s_waitcnt vmcnt(" #n ")" ::: "memory")
; #define PG8_WAIT_L(n) asm volatile("s_waitcnt lgkmcnt(" #n ")" ::: "memory")
; #define PG8_BAR __builtin_amdgcn_s_barrier()
; #define PG8_SCHED __builtin_amdgcn_sched_barrier(0)
; template <class Epi, class Sched, bool ALIGN_EPI, int LMASK = -1, int LMASKB = LMASK>
; __device__ __forceinline__ void gemm_phase(PG8_LAS unsigned char* lds, const Gemm g, const Sched& S, const Epi& E) {
;     ...
;             PG8_LDA(At, 1, 1); PG8_STAGE(PG8_SB(1, 0), b3, voffB); PG8_STAGE(PG8_SB(1, 1), b3 + hstepB, voffB); PG8_STAGE(PG8_SA(1, 0), a3, voffA);
;             PG8_WAIT_V(8); PG8_WAIT_L(0); PG8_BAR; PG8_MMA(1, 0, At, B0); PG8_MMA(1, 1, At, B1); PG8_BAR; PG8_SCHED;
;         }
;         if constexpr (ALIGN_EPI) { if (wr == 0) PG8_BAR; }
;         E(acc, cur, wr, wc, fr, fq);
;         if (!has_next) break;
	s_setprio 0
	s_add_i32 s34, s51, s38
	v_lshl_add_u64 v[146:147], v[146:147], 0, s[80:81]
	s_mov_b32 m0, s34
	ds_read_b128 v[188:191], v151 offset:49152
	ds_read_b128 v[206:209], v151 offset:50176
	ds_read_b128 v[218:221], v151 offset:51200
	ds_read_b128 v[222:225], v151 offset:52224
	ds_read_b128 v[226:229], v151 offset:53248
	ds_read_b128 v[230:233], v151 offset:54272
	ds_read_b128 v[234:237], v151 offset:55296
	ds_read_b128 v[238:241], v151 offset:56320
	global_load_lds_dwordx4 v[146:147], off
	s_add_i32 m0, s34, 0x2000
	s_add_u32 s30, s30, 0x100800
	v_lshl_add_u64 v[146:147], v[176:177], 0, s[80:81]
	s_addc_u32 s31, s31, 0
	s_add_i32 s34, s52, s38
	global_load_lds_dwordx4 v[146:147], off
	v_lshl_add_u64 v[146:147], s[30:31], 0, v[134:135]
	s_mov_b32 m0, s34
	s_nop 0
	global_load_lds_dwordx4 v[146:147], off
	v_lshl_add_u64 v[146:147], s[30:31], 0, v[136:137]
	s_add_i32 m0, s34, 0x2000
	s_nop 0
	global_load_lds_dwordx4 v[146:147], off
	v_lshl_add_u64 v[146:147], v[194:195], 0, s[80:81]
	s_mov_b32 m0, s42
	s_nop 0
	global_load_lds_dwordx4 v[146:147], off
	v_lshl_add_u64 v[146:147], v[210:211], 0, s[80:81]
	s_mov_b32 m0, s43
	s_nop 0
	global_load_lds_dwordx4 v[146:147], off
	s_waitcnt vmcnt(8)
	s_waitcnt lgkmcnt(0)
	s_setprio 1
	s_barrier
	v_mfma_f32_16x16x32_bf16 v[62:65], v[130:133], v[188:191], v[62:65]
	v_mfma_f32_16x16x32_bf16 v[58:61], v[152:155], v[188:191], v[58:61]
	v_mfma_f32_16x16x32_bf16 v[46:49], v[130:133], v[218:221], v[46:49]
	v_mfma_f32_16x16x32_bf16 v[42:45], v[152:155], v[218:221], v[42:45]
	v_mfma_f32_16x16x32_bf16 v[30:33], v[130:133], v[226:229], v[30:33]
	v_mfma_f32_16x16x32_bf16 v[26:29], v[152:155], v[226:229], v[26:29]
	v_mfma_f32_16x16x32_bf16 v[14:17], v[130:133], v[234:237], v[14:17]
	v_mfma_f32_16x16x32_bf16 v[10:13], v[152:155], v[234:237], v[10:13]
	v_mfma_f32_16x16x32_bf16 v[62:65], v[142:145], v[206:209], v[62:65]
	v_mfma_f32_16x16x32_bf16 v[58:61], v[156:159], v[206:209], v[58:61]
	v_mfma_f32_16x16x32_bf16 v[46:49], v[142:145], v[222:225], v[46:49]
	v_mfma_f32_16x16x32_bf16 v[42:45], v[156:159], v[222:225], v[42:45]
	v_mfma_f32_16x16x32_bf16 v[30:33], v[142:145], v[230:233], v[30:33]
	v_mfma_f32_16x16x32_bf16 v[26:29], v[156:159], v[230:233], v[26:29]
	v_mfma_f32_16x16x32_bf16 v[14:17], v[142:145], v[238:241], v[14:17]
	v_mfma_f32_16x16x32_bf16 v[10:13], v[156:159], v[238:241], v[10:13]
	v_mfma_f32_16x16x32_bf16 v[54:57], v[160:163], v[188:191], v[54:57]
	v_mfma_f32_16x16x32_bf16 v[50:53], v[168:171], v[188:191], v[50:53]
	v_mfma_f32_16x16x32_bf16 v[38:41], v[160:163], v[218:221], v[38:41]
	v_mfma_f32_16x16x32_bf16 v[34:37], v[168:171], v[218:221], v[34:37]
	v_mfma_f32_16x16x32_bf16 v[22:25], v[160:163], v[226:229], v[22:25]
	v_mfma_f32_16x16x32_bf16 v[18:21], v[168:171], v[226:229], v[18:21]
	v_mfma_f32_16x16x32_bf16 v[6:9], v[160:163], v[234:237], v[6:9]
	v_mfma_f32_16x16x32_bf16 v[2:5], v[168:171], v[234:237], v[2:5]
	v_mfma_f32_16x16x32_bf16 v[54:57], v[164:167], v[206:209], v[54:57]
	v_mfma_f32_16x16x32_bf16 v[50:53], v[172:175], v[206:209], v[50:53]
	v_mfma_f32_16x16x32_bf16 v[38:41], v[164:167], v[222:225], v[38:41]
	v_mfma_f32_16x16x32_bf16 v[34:37], v[172:175], v[222:225], v[34:37]
	v_mfma_f32_16x16x32_bf16 v[22:25], v[164:167], v[230:233], v[22:25]
	v_mfma_f32_16x16x32_bf16 v[18:21], v[172:175], v[230:233], v[18:21]
	v_mfma_f32_16x16x32_bf16 v[6:9], v[164:167], v[238:241], v[6:9]
	v_mfma_f32_16x16x32_bf16 v[2:5], v[172:175], v[238:241], v[2:5]
	s_barrier
	s_setprio 0
	s_add_i32 s50, s50, 2
	s_add_u32 s28, s28, 0x1000
	s_addc_u32 s29, s29, 0
	s_add_u32 s48, s48, 0x1000
	s_addc_u32 s49, s49, 0
	s_cmp_gt_u32 s50, 61
	s_cbranch_scc0 .LBB0_580
	s_and_b64 vcc, exec, s[14:15]
	s_cbranch_vccz .LBB0_583
	s_barrier

; #define PG8_STAGE(bufoff, gbase, voff) do { _Pragma("unroll") for (int _i = 0; _i < 2; ++_i) \
;         __builtin_amdgcn_global_load_lds((const unsigned*)((const char*)(gbase) + (voff)[_i]), (PG8_LAS unsigned*)(lds + (bufoff) + ldsw + _i * 8192), 16, 0, 0); } while (0)
; #define PG8_LDA(dst, b, h) do { _Pragma("unroll") for (int m = 0; m < 4; ++m) _Pragma("unroll") for (int k = 0; k < 2; ++k) dst[m][k] = *(const PG8_LAS bf16x8*)(lds + PG8_SA(b, h) + aoff + m * 2048 + k * 1024); } while (0)
; #define PG8_LDB(dst, b, h) do { _Pragma("unroll") for (int n = 0; n < 2; ++n) _Pragma("unroll") for (int k = 0; k < 2; ++k) dst[n][k] = *(const PG8_LAS bf16x8*)(lds + PG8_SB(b, h) + boff + n * 2048 + k * 1024); } while (0)
; #define PG8_MMA(ai, bj, At, Bt) do { __builtin_amdgcn_s_setprio(1); _Pragma("unroll") for (int m = 0; m < 4; ++m) _Pragma("unroll") for (int n = 0; n < 2; ++n) _Pragma("unroll") for (int k = 0; k < 2; ++k) \
;         acc[ai][bj][m][n] = __builtin_amdgcn_mfma_f32_16x16x32_bf16(Bt[n][k], At[m][k], acc[ai][bj][m][n], 0, 0, 0); __builtin_amdgcn_s_setprio(0); } while (0)
; #define PG8_WAIT_V(n) asm volatile("s_waitcnt vmcnt(" #n ")" ::: "memory")
; #define PG8_WAIT_L(n) asm volatile("s_waitcnt lgkmcnt(" #n ")" ::: "memory")
; #define PG8_BAR __builtin_amdgcn_s_barrier()
; #define PG8_SCHED __builtin_amdgcn_sched_barrier(0)
; template <class Epi, class Sched, bool ALIGN_EPI, int LMASK = -1, int LMASKB = LMASK>
; __device__ __forceinline__ void gemm_phase(PG8_LAS unsigned char* lds, const Gemm g, const Sched& S, const Epi& E) {
;     ...
;             PG8_LDB(B0, 0, 0); PG8_LDB(B1, 0, 1); PG8_SCHED; PG8_LDA(At, 0, 0); PG8_STAGE(PG8_SA(1, 1), a1 + hstepA, voffA);
;             PG8_WAIT_V(8); PG8_WAIT_L(0); PG8_BAR; PG8_MMA(0, 0, At, B0); PG8_MMA(0, 1, At, B1); PG8_BAR; PG8_SCHED;
;             PG8_LDA(At, 0, 1); PG8_STAGE(PG8_SB(0, 0), b2, voffB); PG8_STAGE(PG8_SB(0, 1), b2 + hstepB, voffB); PG8_STAGE(PG8_SA(0, 0), a2, voffA);
;             PG8_WAIT_V(8); PG8_WAIT_L(0); PG8_BAR; PG8_MMA(1, 0, At, B0); PG8_MMA(1, 1, At, B1); PG8_BAR; PG8_SCHED;
.LBB0_678:
	s_add_u32 s26, s24, 0xfff00800
	s_addc_u32 s27, s25, -1
	s_add_i32 s50, 0, 0x10000
	s_cmp_eq_u32 s49, 60
	s_cselect_b32 s29, s1, s27
	s_cselect_b32 s28, s2, s26
	s_cselect_b32 s27, s15, s48
	s_cselect_b32 s26, s17, s47
	s_add_i32 s52, 0, 0x14000
	v_add_u32_e32 v154, s50, v143
	v_add_u32_e32 v170, s52, v143
	ds_read_b128 v[138:141], v154
	ds_read_b128 v[146:149], v154 offset:1024
	ds_read_b128 v[150:153], v154 offset:2048
	ds_read_b128 v[154:157], v154 offset:3072
	ds_read_b128 v[158:161], v170
	ds_read_b128 v[162:165], v170 offset:1024
	ds_read_b128 v[166:169], v170 offset:2048
	ds_read_b128 v[170:173], v170 offset:3072
	v_lshl_add_u64 v[194:195], s[24:25], 0, v[134:135]
	s_add_i32 m0, s23, 0xc000
	ds_read_b128 v[174:177], v145
	ds_read_b128 v[188:191], v145 offset:1024
	ds_read_b128 v[206:209], v145 offset:2048
	ds_read_b128 v[218:221], v145 offset:3072
	ds_read_b128 v[222:225], v145 offset:4096
	ds_read_b128 v[226:229], v145 offset:5120
	ds_read_b128 v[230:233], v145 offset:6144
	ds_read_b128 v[234:237], v145 offset:7168
	global_load_lds_dwordx4 v[194:195], off
	v_lshl_add_u64 v[194:195], s[24:25], 0, v[136:137]
	s_add_i32 m0, s23, 0xe000
	s_nop 0
	global_load_lds_dwordx4 v[194:195], off
	s_waitcnt vmcnt(8)
	s_waitcnt lgkmcnt(0)
	s_setprio 1
	s_barrier
	v_mfma_f32_16x16x32_bf16 v[126:129], v[138:141], v[174:177], v[126:129]
	v_mfma_f32_16x16x32_bf16 v[122:125], v[150:153], v[174:177], v[122:125]
	v_mfma_f32_16x16x32_bf16 v[110:113], v[138:141], v[206:209], v[110:113]
	v_mfma_f32_16x16x32_bf16 v[106:109], v[150:153], v[206:209], v[106:109]
	v_mfma_f32_16x16x32_bf16 v[94:97], v[138:141], v[222:225], v[94:97]
	v_mfma_f32_16x16x32_bf16 v[90:93], v[150:153], v[222:225], v[90:93]
	v_mfma_f32_16x16x32_bf16 v[78:81], v[138:141], v[230:233], v[78:81]
	v_mfma_f32_16x16x32_bf16 v[74:77], v[150:153], v[230:233], v[74:77]
	v_mfma_f32_16x16x32_bf16 v[126:129], v[146:149], v[188:191], v[126:129]
	v_mfma_f32_16x16x32_bf16 v[122:125], v[154:157], v[188:191], v[122:125]
	v_mfma_f32_16x16x32_bf16 v[110:113], v[146:149], v[218:221], v[110:113]
	v_mfma_f32_16x16x32_bf16 v[106:109], v[154:157], v[218:221], v[106:109]
	v_mfma_f32_16x16x32_bf16 v[94:97], v[146:149], v[226:229], v[94:97]
	v_mfma_f32_16x16x32_bf16 v[90:93], v[154:157], v[226:229], v[90:93]
	v_mfma_f32_16x16x32_bf16 v[78:81], v[146:149], v[234:237], v[78:81]
	v_mfma_f32_16x16x32_bf16 v[74:77], v[154:157], v[234:237], v[74:77]
	v_mfma_f32_16x16x32_bf16 v[118:121], v[158:161], v[174:177], v[118:121]
	v_mfma_f32_16x16x32_bf16 v[114:117], v[166:169], v[174:177], v[114:117]
	v_mfma_f32_16x16x32_bf16 v[102:105], v[158:161], v[206:209], v[102:105]
	v_mfma_f32_16x16x32_bf16 v[98:101], v[166:169], v[206:209], v[98:101]
	v_mfma_f32_16x16x32_bf16 v[86:89], v[158:161], v[222:225], v[86:89]
	v_mfma_f32_16x16x32_bf16 v[82:85], v[166:169], v[222:225], v[82:85]
	v_mfma_f32_16x16x32_bf16 v[70:73], v[158:161], v[230:233], v[70:73]
	v_mfma_f32_16x16x32_bf16 v[66:69], v[166:169], v[230:233], v[66:69]
	v_mfma_f32_16x16x32_bf16 v[118:121], v[162:165], v[188:191], v[118:121]
	v_mfma_f32_16x16x32_bf16 v[114:117], v[170:173], v[188:191], v[114:117]
	v_mfma_f32_16x16x32_bf16 v[102:105], v[162:165], v[218:221], v[102:105]
	v_mfma_f32_16x16x32_bf16 v[98:101], v[170:173], v[218:221], v[98:101]
	v_mfma_f32_16x16x32_bf16 v[86:89], v[162:165], v[226:229], v[86:89]
	v_mfma_f32_16x16x32_bf16 v[82:85], v[170:173], v[226:229], v[82:85]
	v_mfma_f32_16x16x32_bf16 v[70:73], v[162:165], v[234:237], v[70:73]
	v_mfma_f32_16x16x32_bf16 v[66:69], v[170:173], v[234:237], v[66:69]
	s_barrier
	s_setprio 0
	s_add_i32 s50, s50, s38
	v_lshl_add_u64 v[194:195], s[26:27], 0, v[130:131]
	s_mov_b32 m0, s50
	ds_read_b128 v[174:177], v145 offset:16384
	ds_read_b128 v[188:191], v145 offset:17408
	ds_read_b128 v[206:209], v145 offset:18432
	ds_read_b128 v[218:221], v145 offset:19456
	ds_read_b128 v[222:225], v145 offset:20480
	ds_read_b128 v[226:229], v145 offset:21504
	ds_read_b128 v[230:233], v145 offset:22528
	ds_read_b128 v[234:237], v145 offset:23552
	global_load_lds_dwordx4 v[194:195], off
	s_add_i32 m0, s50, 0x2000
	s_add_u32 s50, s26, 0x100000
	v_lshl_add_u64 v[210:211], s[26:27], 0, v[132:133]
	s_addc_u32 s51, s27, 0
	s_add_i32 s52, s52, s38
	global_load_lds_dwordx4 v[210:211], off
	v_lshl_add_u64 v[212:213], s[50:51], 0, v[130:131]
	s_mov_b32 m0, s52
	v_lshl_add_u64 v[238:239], s[28:29], 0, v[132:133]
	global_load_lds_dwordx4 v[212:213], off
	v_lshl_add_u64 v[212:213], s[50:51], 0, v[132:133]
	s_add_i32 m0, s52, 0x2000
	s_nop 0
	global_load_lds_dwordx4 v[212:213], off
	v_lshl_add_u64 v[212:213], s[28:29], 0, v[130:131]
	s_mov_b32 m0, s23
	s_nop 0
	global_load_lds_dwordx4 v[212:213], off
	s_mov_b32 m0, s39
	s_nop 0
	global_load_lds_dwordx4 v[238:239], off
	s_waitcnt vmcnt(8)
	s_waitcnt lgkmcnt(0)
	s_setprio 1
	s_barrier
; #define PG8_STAGE(bufoff, gbase, voff) do { _Pragma("unroll") for (int _i = 0; _i < 2; ++_i) \
;         __builtin_amdgcn_global_load_lds((const unsigned*)((const char*)(gbase) + (voff)[_i]), (PG8_LAS unsigned*)(lds + (bufoff) + ldsw + _i * 8192), 16, 0, 0); } while (0)
; #define PG8_LDA(dst, b, h) do { _Pragma("unroll") for (int m = 0; m < 4; ++m) _Pragma("unroll") for (int k = 0; k < 2; ++k) dst[m][k] = *(const PG8_LAS bf16x8*)(lds + PG8_SA(b, h) + aoff + m * 2048 + k * 1024); } while (0)
; #define PG8_LDB(dst, b, h) do { _Pragma("unroll") for (int n = 0; n < 2; ++n) _Pragma("unroll") for (int k = 0; k < 2; ++k) dst[n][k] = *(const PG8_LAS bf16x8*)(lds + PG8_SB(b, h) + boff + n * 2048 + k * 1024); } while (0)
; #define PG8_MMA(ai, bj, At, Bt) do { __builtin_amdgcn_s_setprio(1); _Pragma("unroll") for (int m = 0; m < 4; ++m) _Pragma("unroll") for (int n = 0; n < 2; ++n) _Pragma("unroll") for (int k = 0; k < 2; ++k) \
;         acc[ai][bj][m][n] = __builtin_amdgcn_mfma_f32_16x16x32_bf16(Bt[n][k], At[m][k], acc[ai][bj][m][n], 0, 0, 0); __builtin_amdgcn_s_setprio(0); } while (0)
; #define PG8_WAIT_V(n) asm volatile("s_waitcnt vmcnt(" #n ")" ::: "memory")
; #define PG8_WAIT_L(n) asm volatile("s_waitcnt lgkmcnt(" #n ")" ::: "memory")
; #define PG8_BAR __builtin_amdgcn_s_barrier()
; #define PG8_SCHED __builtin_amdgcn_sched_barrier(0)
; template <class Epi, class Sched, bool ALIGN_EPI, int LMASK = -1, int LMASKB = LMASK>
; __device__ __forceinline__ void gemm_phase(PG8_LAS unsigned char* lds, const Gemm g, const Sched& S, const Epi& E) {
;     ...
;             PG8_WAIT_V(8); PG8_WAIT_L(0); PG8_BAR; PG8_MMA(1, 0, At, B0); PG8_MMA(1, 1, At, B1); PG8_BAR; PG8_SCHED;
;             PG8_LDB(B0, 1, 0); PG8_LDB(B1, 1, 1); PG8_SCHED; PG8_LDA(At, 1, 0); PG8_STAGE(PG8_SA(0, 1), a2 + hstepA, voffA);
;             PG8_WAIT_V(8); PG8_WAIT_L(0); PG8_BAR; PG8_MMA(0, 0, At, B0); PG8_MMA(0, 1, At, B1); PG8_BAR; PG8_SCHED;
;             PG8_LDA(At, 1, 1); PG8_STAGE(PG8_SB(1, 0), b3, voffB); PG8_STAGE(PG8_SB(1, 1), b3 + hstepB, voffB); PG8_STAGE(PG8_SA(1, 0), a3, voffA);
	v_mfma_f32_16x16x32_bf16 v[62:65], v[138:141], v[174:177], v[62:65]
	v_mfma_f32_16x16x32_bf16 v[58:61], v[150:153], v[174:177], v[58:61]
	v_mfma_f32_16x16x32_bf16 v[46:49], v[138:141], v[206:209], v[46:49]
	v_mfma_f32_16x16x32_bf16 v[42:45], v[150:153], v[206:209], v[42:45]
	v_mfma_f32_16x16x32_bf16 v[30:33], v[138:141], v[222:225], v[30:33]
	v_mfma_f32_16x16x32_bf16 v[26:29], v[150:153], v[222:225], v[26:29]
	v_mfma_f32_16x16x32_bf16 v[14:17], v[138:141], v[230:233], v[14:17]
	v_mfma_f32_16x16x32_bf16 v[10:13], v[150:153], v[230:233], v[10:13]
	v_mfma_f32_16x16x32_bf16 v[62:65], v[146:149], v[188:191], v[62:65]
	v_mfma_f32_16x16x32_bf16 v[58:61], v[154:157], v[188:191], v[58:61]
	v_mfma_f32_16x16x32_bf16 v[46:49], v[146:149], v[218:221], v[46:49]
	v_mfma_f32_16x16x32_bf16 v[42:45], v[154:157], v[218:221], v[42:45]
	v_mfma_f32_16x16x32_bf16 v[30:33], v[146:149], v[226:229], v[30:33]
	v_mfma_f32_16x16x32_bf16 v[26:29], v[154:157], v[226:229], v[26:29]
	v_mfma_f32_16x16x32_bf16 v[14:17], v[146:149], v[234:237], v[14:17]
	v_mfma_f32_16x16x32_bf16 v[10:13], v[154:157], v[234:237], v[10:13]
	v_mfma_f32_16x16x32_bf16 v[54:57], v[158:161], v[174:177], v[54:57]
	v_mfma_f32_16x16x32_bf16 v[50:53], v[166:169], v[174:177], v[50:53]
	v_mfma_f32_16x16x32_bf16 v[38:41], v[158:161], v[206:209], v[38:41]
	v_mfma_f32_16x16x32_bf16 v[34:37], v[166:169], v[206:209], v[34:37]
	v_mfma_f32_16x16x32_bf16 v[22:25], v[158:161], v[222:225], v[22:25]
	v_mfma_f32_16x16x32_bf16 v[18:21], v[166:169], v[222:225], v[18:21]
	v_mfma_f32_16x16x32_bf16 v[6:9], v[158:161], v[230:233], v[6:9]
	v_mfma_f32_16x16x32_bf16 v[2:5], v[166:169], v[230:233], v[2:5]
	v_mfma_f32_16x16x32_bf16 v[54:57], v[162:165], v[188:191], v[54:57]
	v_mfma_f32_16x16x32_bf16 v[50:53], v[170:173], v[188:191], v[50:53]
	v_mfma_f32_16x16x32_bf16 v[38:41], v[162:165], v[218:221], v[38:41]
	v_mfma_f32_16x16x32_bf16 v[34:37], v[170:173], v[218:221], v[34:37]
	v_mfma_f32_16x16x32_bf16 v[22:25], v[162:165], v[226:229], v[22:25]
	v_mfma_f32_16x16x32_bf16 v[18:21], v[170:173], v[226:229], v[18:21]
	v_mfma_f32_16x16x32_bf16 v[6:9], v[162:165], v[234:237], v[6:9]
	v_mfma_f32_16x16x32_bf16 v[2:5], v[170:173], v[234:237], v[2:5]
	s_barrier
	s_setprio 0
	s_add_i32 s50, 0, 0x18000
	s_add_i32 s51, 0, 0x1c000
	v_add_u32_e32 v154, s50, v143
	v_add_u32_e32 v170, s51, v143
	ds_read_b128 v[138:141], v154
	ds_read_b128 v[146:149], v154 offset:1024
	ds_read_b128 v[150:153], v154 offset:2048
	ds_read_b128 v[154:157], v154 offset:3072
	ds_read_b128 v[158:161], v170
	ds_read_b128 v[162:165], v170 offset:1024
	ds_read_b128 v[166:169], v170 offset:2048
	ds_read_b128 v[170:173], v170 offset:3072
	s_add_u32 s28, s28, 0x100000
	s_addc_u32 s29, s29, 0
	s_mov_b32 m0, s40
	v_lshl_add_u64 v[240:241], s[28:29], 0, v[130:131]
	ds_read_b128 v[174:177], v145 offset:32768
	ds_read_b128 v[188:191], v145 offset:33792
	ds_read_b128 v[206:209], v145 offset:34816
	ds_read_b128 v[218:221], v145 offset:35840
	ds_read_b128 v[222:225], v145 offset:36864
	ds_read_b128 v[226:229], v145 offset:37888
	ds_read_b128 v[230:233], v145 offset:38912
	ds_read_b128 v[234:237], v145 offset:39936
	global_load_lds_dwordx4 v[240:241], off
	v_lshl_add_u64 v[240:241], s[28:29], 0, v[132:133]
	s_mov_b32 m0, s41
	s_nop 0
	global_load_lds_dwordx4 v[240:241], off
	s_waitcnt vmcnt(8)
	s_waitcnt lgkmcnt(0)
	s_setprio 1
	s_barrier
	v_mfma_f32_16x16x32_bf16 v[126:129], v[138:141], v[174:177], v[126:129]
	v_mfma_f32_16x16x32_bf16 v[122:125], v[150:153], v[174:177], v[122:125]
	v_mfma_f32_16x16x32_bf16 v[110:113], v[138:141], v[206:209], v[110:113]
	v_mfma_f32_16x16x32_bf16 v[106:109], v[150:153], v[206:209], v[106:109]
	v_mfma_f32_16x16x32_bf16 v[94:97], v[138:141], v[222:225], v[94:97]
	v_mfma_f32_16x16x32_bf16 v[90:93], v[150:153], v[222:225], v[90:93]
	v_mfma_f32_16x16x32_bf16 v[78:81], v[138:141], v[230:233], v[78:81]
	v_mfma_f32_16x16x32_bf16 v[74:77], v[150:153], v[230:233], v[74:77]
	v_mfma_f32_16x16x32_bf16 v[126:129], v[146:149], v[188:191], v[126:129]
	v_mfma_f32_16x16x32_bf16 v[122:125], v[154:157], v[188:191], v[122:125]
	v_mfma_f32_16x16x32_bf16 v[110:113], v[146:149], v[218:221], v[110:113]
	v_mfma_f32_16x16x32_bf16 v[106:109], v[154:157], v[218:221], v[106:109]
	v_mfma_f32_16x16x32_bf16 v[94:97], v[146:149], v[226:229], v[94:97]
	v_mfma_f32_16x16x32_bf16 v[90:93], v[154:157], v[226:229], v[90:93]
	v_mfma_f32_16x16x32_bf16 v[78:81], v[146:149], v[234:237], v[78:81]
	v_mfma_f32_16x16x32_bf16 v[74:77], v[154:157], v[234:237], v[74:77]
	v_mfma_f32_16x16x32_bf16 v[118:121], v[158:161], v[174:177], v[118:121]
	v_mfma_f32_16x16x32_bf16 v[114:117], v[166:169], v[174:177], v[114:117]
	v_mfma_f32_16x16x32_bf16 v[102:105], v[158:161], v[206:209], v[102:105]
	v_mfma_f32_16x16x32_bf16 v[98:101], v[166:169], v[206:209], v[98:101]
	v_mfma_f32_16x16x32_bf16 v[86:89], v[158:161], v[222:225], v[86:89]
	v_mfma_f32_16x16x32_bf16 v[82:85], v[166:169], v[222:225], v[82:85]
	v_mfma_f32_16x16x32_bf16 v[70:73], v[158:161], v[230:233], v[70:73]
	v_mfma_f32_16x16x32_bf16 v[66:69], v[166:169], v[230:233], v[66:69]
	v_mfma_f32_16x16x32_bf16 v[118:121], v[162:165], v[188:191], v[118:121]
	v_mfma_f32_16x16x32_bf16 v[114:117], v[170:173], v[188:191], v[114:117]
	v_mfma_f32_16x16x32_bf16 v[102:105], v[162:165], v[218:221], v[102:105]
	v_mfma_f32_16x16x32_bf16 v[98:101], v[170:173], v[218:221], v[98:101]
	v_mfma_f32_16x16x32_bf16 v[86:89], v[162:165], v[226:229], v[86:89]
	v_mfma_f32_16x16x32_bf16 v[82:85], v[170:173], v[226:229], v[82:85]
	v_mfma_f32_16x16x32_bf16 v[70:73], v[162:165], v[234:237], v[70:73]
	v_mfma_f32_16x16x32_bf16 v[66:69], v[170:173], v[234:237], v[66:69]
	s_barrier
; #define PG8_STAGE(bufoff, gbase, voff) do { _Pragma("unroll") for (int _i = 0; _i < 2; ++_i) \
;         __builtin_amdgcn_global_load_lds((const unsigned*)((const char*)(gbase) + (voff)[_i]), (PG8_LAS unsigned*)(lds + (bufoff) + ldsw + _i * 8192), 16, 0, 0); } while (0)
; #define PG8_LDA(dst, b, h) do { _Pragma("unroll") for (int m = 0; m < 4; ++m) _Pragma("unroll") for (int k = 0; k < 2; ++k) dst[m][k] = *(const PG8_LAS bf16x8*)(lds + PG8_SA(b, h) + aoff + m * 2048 + k * 1024); } while (0)
; #define PG8_MMA(ai, bj, At, Bt) do { __builtin_amdgcn_s_setprio(1); _Pragma("unroll") for (int m = 0; m < 4; ++m) _Pragma("unroll") for (int n = 0; n < 2; ++n) _Pragma("unroll") for (int k = 0; k < 2; ++k) \
;         acc[ai][bj][m][n] = __builtin_amdgcn_mfma_f32_16x16x32_bf16(Bt[n][k], At[m][k], acc[ai][bj][m][n], 0, 0, 0); __builtin_amdgcn_s_setprio(0); } while (0)
; #define PG8_WAIT_V(n) asm volatile("s_waitcnt vmcnt(" #n ")" ::: "memory")
; #define PG8_WAIT_L(n) asm volatile("s_waitcnt lgkmcnt(" #n ")" ::: "memory")
; #define PG8_BAR __builtin_amdgcn_s_barrier()
; #define PG8_SCHED __builtin_amdgcn_sched_barrier(0)
; template <class Epi, class Sched, bool ALIGN_EPI, int LMASK = -1, int LMASKB = LMASK>
; __device__ __forceinline__ void gemm_phase(PG8_LAS unsigned char* lds, const Gemm g, const Sched& S, const Epi& E) {
;     ...
;             PG8_LDA(At, 1, 1); PG8_STAGE(PG8_SB(1, 0), b3, voffB); PG8_STAGE(PG8_SB(1, 1), b3 + hstepB, voffB); PG8_STAGE(PG8_SA(1, 0), a3, voffA);
;             PG8_WAIT_V(8); PG8_WAIT_L(0); PG8_BAR; PG8_MMA(1, 0, At, B0); PG8_MMA(1, 1, At, B1); PG8_BAR; PG8_SCHED;
;         }
;         if constexpr (ALIGN_EPI) { if (wr == 0) PG8_BAR; }
	s_setprio 0
	s_add_i32 s28, s50, s38
	v_lshl_add_u64 v[194:195], v[194:195], 0, s[80:81]
	s_mov_b32 m0, s28
	ds_read_b128 v[174:177], v145 offset:49152
	ds_read_b128 v[188:191], v145 offset:50176
	ds_read_b128 v[206:209], v145 offset:51200
	ds_read_b128 v[218:221], v145 offset:52224
	ds_read_b128 v[222:225], v145 offset:53248
	ds_read_b128 v[226:229], v145 offset:54272
	ds_read_b128 v[230:233], v145 offset:55296
	ds_read_b128 v[234:237], v145 offset:56320
	global_load_lds_dwordx4 v[194:195], off
	s_add_i32 m0, s28, 0x2000
	s_add_u32 s26, s26, 0x100800
	v_lshl_add_u64 v[194:195], v[210:211], 0, s[80:81]
	s_addc_u32 s27, s27, 0
	s_add_i32 s28, s51, s38
	global_load_lds_dwordx4 v[194:195], off
	v_lshl_add_u64 v[194:195], s[26:27], 0, v[130:131]
	s_mov_b32 m0, s28
	s_nop 0
	global_load_lds_dwordx4 v[194:195], off
	v_lshl_add_u64 v[194:195], s[26:27], 0, v[132:133]
	s_add_i32 m0, s28, 0x2000
	s_nop 0
	global_load_lds_dwordx4 v[194:195], off
	v_lshl_add_u64 v[194:195], v[212:213], 0, s[80:81]
	s_mov_b32 m0, s42
	s_nop 0
	global_load_lds_dwordx4 v[194:195], off
	v_lshl_add_u64 v[194:195], v[238:239], 0, s[80:81]
	s_mov_b32 m0, s43
	s_nop 0
	global_load_lds_dwordx4 v[194:195], off
	s_waitcnt vmcnt(8)
	s_waitcnt lgkmcnt(0)
	s_setprio 1
	s_barrier
	v_mfma_f32_16x16x32_bf16 v[62:65], v[138:141], v[174:177], v[62:65]
	v_mfma_f32_16x16x32_bf16 v[58:61], v[150:153], v[174:177], v[58:61]
	v_mfma_f32_16x16x32_bf16 v[46:49], v[138:141], v[206:209], v[46:49]
	v_mfma_f32_16x16x32_bf16 v[42:45], v[150:153], v[206:209], v[42:45]
	v_mfma_f32_16x16x32_bf16 v[30:33], v[138:141], v[222:225], v[30:33]
	v_mfma_f32_16x16x32_bf16 v[26:29], v[150:153], v[222:225], v[26:29]
	v_mfma_f32_16x16x32_bf16 v[14:17], v[138:141], v[230:233], v[14:17]
	v_mfma_f32_16x16x32_bf16 v[10:13], v[150:153], v[230:233], v[10:13]
	v_mfma_f32_16x16x32_bf16 v[62:65], v[146:149], v[188:191], v[62:65]
	v_mfma_f32_16x16x32_bf16 v[58:61], v[154:157], v[188:191], v[58:61]
	v_mfma_f32_16x16x32_bf16 v[46:49], v[146:149], v[218:221], v[46:49]
	v_mfma_f32_16x16x32_bf16 v[42:45], v[154:157], v[218:221], v[42:45]
	v_mfma_f32_16x16x32_bf16 v[30:33], v[146:149], v[226:229], v[30:33]
	v_mfma_f32_16x16x32_bf16 v[26:29], v[154:157], v[226:229], v[26:29]
	v_mfma_f32_16x16x32_bf16 v[14:17], v[146:149], v[234:237], v[14:17]
	v_mfma_f32_16x16x32_bf16 v[10:13], v[154:157], v[234:237], v[10:13]
	v_mfma_f32_16x16x32_bf16 v[54:57], v[158:161], v[174:177], v[54:57]
	v_mfma_f32_16x16x32_bf16 v[50:53], v[166:169], v[174:177], v[50:53]
	v_mfma_f32_16x16x32_bf16 v[38:41], v[158:161], v[206:209], v[38:41]
	v_mfma_f32_16x16x32_bf16 v[34:37], v[166:169], v[206:209], v[34:37]
	v_mfma_f32_16x16x32_bf16 v[22:25], v[158:161], v[222:225], v[22:25]
	v_mfma_f32_16x16x32_bf16 v[18:21], v[166:169], v[222:225], v[18:21]
	v_mfma_f32_16x16x32_bf16 v[6:9], v[158:161], v[230:233], v[6:9]
	v_mfma_f32_16x16x32_bf16 v[2:5], v[166:169], v[230:233], v[2:5]
	v_mfma_f32_16x16x32_bf16 v[54:57], v[162:165], v[188:191], v[54:57]
	v_mfma_f32_16x16x32_bf16 v[50:53], v[170:173], v[188:191], v[50:53]
	v_mfma_f32_16x16x32_bf16 v[38:41], v[162:165], v[218:221], v[38:41]
	v_mfma_f32_16x16x32_bf16 v[34:37], v[170:173], v[218:221], v[34:37]
	v_mfma_f32_16x16x32_bf16 v[22:25], v[162:165], v[226:229], v[22:25]
	v_mfma_f32_16x16x32_bf16 v[18:21], v[170:173], v[226:229], v[18:21]
	v_mfma_f32_16x16x32_bf16 v[6:9], v[162:165], v[234:237], v[6:9]
	v_mfma_f32_16x16x32_bf16 v[2:5], v[170:173], v[234:237], v[2:5]
	s_barrier
	s_setprio 0
	s_add_i32 s49, s49, 2
	s_add_u32 s24, s24, 0x1000
	s_addc_u32 s25, s25, 0
	s_add_u32 s47, s47, 0x1000
	s_addc_u32 s48, s48, 0
	s_cmp_gt_u32 s49, 61
	s_cbranch_scc0 .LBB0_678
	s_and_b64 vcc, exec, s[12:13]
	s_cbranch_vccz .LBB0_681
	s_barrier

; #define PG8_STAGE(bufoff, gbase, voff) do { _Pragma("unroll") for (int _i = 0; _i < 2; ++_i) \
;         __builtin_amdgcn_global_load_lds((const unsigned*)((const char*)(gbase) + (voff)[_i]), (PG8_LAS unsigned*)(lds + (bufoff) + ldsw + _i * 8192), 16, 0, 0); } while (0)
; #define PG8_LDA(dst, b, h) do { _Pragma("unroll") for (int m = 0; m < 4; ++m) _Pragma("unroll") for (int k = 0; k < 2; ++k) dst[m][k] = *(const PG8_LAS bf16x8*)(lds + PG8_SA(b, h) + aoff + m * 2048 + k * 1024); } while (0)
; #define PG8_LDB(dst, b, h) do { _Pragma("unroll") for (int n = 0; n < 2; ++n) _Pragma("unroll") for (int k = 0; k < 2; ++k) dst[n][k] = *(const PG8_LAS bf16x8*)(lds + PG8_SB(b, h) + boff + n * 2048 + k * 1024); } while (0)
; #define PG8_MMA(ai, bj, At, Bt) do { __builtin_amdgcn_s_setprio(1); _Pragma("unroll") for (int m = 0; m < 4; ++m) _Pragma("unroll") for (int n = 0; n < 2; ++n) _Pragma("unroll") for (int k = 0; k < 2; ++k) \
;         acc[ai][bj][m][n] = __builtin_amdgcn_mfma_f32_16x16x32_bf16(Bt[n][k], At[m][k], acc[ai][bj][m][n], 0, 0, 0); __builtin_amdgcn_s_setprio(0); } while (0)
; #define PG8_WAIT_V(n) asm volatile("s_waitcnt vmcnt(" #n ")" ::: "memory")
; #define PG8_WAIT_L(n) asm volatile("s_waitcnt lgkmcnt(" #n ")" ::: "memory")
; #define PG8_BAR __builtin_amdgcn_s_barrier()
; #define PG8_SCHED __builtin_amdgcn_sched_barrier(0)
; template <class Epi, class Sched, bool ALIGN_EPI, int LMASK = -1, int LMASKB = LMASK>
; __device__ __forceinline__ void gemm_phase(PG8_LAS unsigned char* lds, const Gemm g, const Sched& S, const Epi& E) {
;     ...
;             PG8_LDB(B0, 0, 0); PG8_LDB(B1, 0, 1); PG8_SCHED; PG8_LDA(At, 0, 0); PG8_STAGE(PG8_SA(1, 1), a1 + hstepA, voffA);
;             PG8_WAIT_V(8); PG8_WAIT_L(0); PG8_BAR; PG8_MMA(0, 0, At, B0); PG8_MMA(0, 1, At, B1); PG8_BAR; PG8_SCHED;
;             PG8_LDA(At, 0, 1); PG8_STAGE(PG8_SB(0, 0), b2, voffB); PG8_STAGE(PG8_SB(0, 1), b2 + hstepB, voffB); PG8_STAGE(PG8_SA(0, 0), a2, voffA);
;             PG8_WAIT_V(8); PG8_WAIT_L(0); PG8_BAR; PG8_MMA(1, 0, At, B0); PG8_MMA(1, 1, At, B1); PG8_BAR; PG8_SCHED;
.LBB0_761:
	s_add_u32 s2, s28, 0xffc00800
	s_addc_u32 s3, s29, -1
	s_add_i32 s51, 0, 0x10000
	s_cmpk_eq_i32 s50, 0xfc
	s_cselect_b32 s31, s19, s3
	s_cselect_b32 s30, s46, s2
	v_add_u32_e32 v146, s51, v149
	s_cselect_b32 s3, s17, s49
	s_cselect_b32 s2, s47, s48
	s_add_i32 s54, 0, 0x14000
	ds_read_b128 v[130:133], v146
	ds_read_b128 v[142:145], v146 offset:1024
	ds_read_b128 v[152:155], v146 offset:2048
	ds_read_b128 v[156:159], v146 offset:3072
	v_add_u32_e32 v146, s54, v149
	ds_read_b128 v[160:163], v146
	ds_read_b128 v[164:167], v146 offset:1024
	ds_read_b128 v[168:171], v146 offset:2048
	ds_read_b128 v[172:175], v146 offset:3072
	v_lshl_add_u64 v[146:147], s[28:29], 0, v[138:139]
	s_add_i32 m0, s25, 0xc000
	ds_read_b128 v[188:191], v151
	ds_read_b128 v[206:209], v151 offset:1024
	ds_read_b128 v[218:221], v151 offset:2048
	ds_read_b128 v[222:225], v151 offset:3072
	ds_read_b128 v[226:229], v151 offset:4096
	ds_read_b128 v[230:233], v151 offset:5120
	ds_read_b128 v[234:237], v151 offset:6144
	ds_read_b128 v[238:241], v151 offset:7168
	global_load_lds_dwordx4 v[146:147], off
	v_lshl_add_u64 v[146:147], s[28:29], 0, v[140:141]
	s_add_i32 m0, s25, 0xe000
	s_nop 0
	global_load_lds_dwordx4 v[146:147], off
	s_waitcnt vmcnt(8)
	s_waitcnt lgkmcnt(0)
	s_setprio 1
	s_barrier
	v_mfma_f32_16x16x32_bf16 v[126:129], v[130:133], v[188:191], v[126:129]
	v_mfma_f32_16x16x32_bf16 v[122:125], v[152:155], v[188:191], v[122:125]
	v_mfma_f32_16x16x32_bf16 v[110:113], v[130:133], v[218:221], v[110:113]
	v_mfma_f32_16x16x32_bf16 v[106:109], v[152:155], v[218:221], v[106:109]
	v_mfma_f32_16x16x32_bf16 v[94:97], v[130:133], v[226:229], v[94:97]
	v_mfma_f32_16x16x32_bf16 v[90:93], v[152:155], v[226:229], v[90:93]
	v_mfma_f32_16x16x32_bf16 v[78:81], v[130:133], v[234:237], v[78:81]
	v_mfma_f32_16x16x32_bf16 v[74:77], v[152:155], v[234:237], v[74:77]
	v_mfma_f32_16x16x32_bf16 v[126:129], v[142:145], v[206:209], v[126:129]
	v_mfma_f32_16x16x32_bf16 v[122:125], v[156:159], v[206:209], v[122:125]
	v_mfma_f32_16x16x32_bf16 v[110:113], v[142:145], v[222:225], v[110:113]
	v_mfma_f32_16x16x32_bf16 v[106:109], v[156:159], v[222:225], v[106:109]
	v_mfma_f32_16x16x32_bf16 v[94:97], v[142:145], v[230:233], v[94:97]
	v_mfma_f32_16x16x32_bf16 v[90:93], v[156:159], v[230:233], v[90:93]
	v_mfma_f32_16x16x32_bf16 v[78:81], v[142:145], v[238:241], v[78:81]
	v_mfma_f32_16x16x32_bf16 v[74:77], v[156:159], v[238:241], v[74:77]
	v_mfma_f32_16x16x32_bf16 v[118:121], v[160:163], v[188:191], v[118:121]
	v_mfma_f32_16x16x32_bf16 v[114:117], v[168:171], v[188:191], v[114:117]
	v_mfma_f32_16x16x32_bf16 v[102:105], v[160:163], v[218:221], v[102:105]
	v_mfma_f32_16x16x32_bf16 v[98:101], v[168:171], v[218:221], v[98:101]
	v_mfma_f32_16x16x32_bf16 v[86:89], v[160:163], v[226:229], v[86:89]
	v_mfma_f32_16x16x32_bf16 v[82:85], v[168:171], v[226:229], v[82:85]
	v_mfma_f32_16x16x32_bf16 v[70:73], v[160:163], v[234:237], v[70:73]
	v_mfma_f32_16x16x32_bf16 v[66:69], v[168:171], v[234:237], v[66:69]
	v_mfma_f32_16x16x32_bf16 v[118:121], v[164:167], v[206:209], v[118:121]
	v_mfma_f32_16x16x32_bf16 v[114:117], v[172:175], v[206:209], v[114:117]
	v_mfma_f32_16x16x32_bf16 v[102:105], v[164:167], v[222:225], v[102:105]
	v_mfma_f32_16x16x32_bf16 v[98:101], v[172:175], v[222:225], v[98:101]
	v_mfma_f32_16x16x32_bf16 v[86:89], v[164:167], v[230:233], v[86:89]
	v_mfma_f32_16x16x32_bf16 v[82:85], v[172:175], v[230:233], v[82:85]
	v_mfma_f32_16x16x32_bf16 v[70:73], v[164:167], v[238:241], v[70:73]
	v_mfma_f32_16x16x32_bf16 v[66:69], v[172:175], v[238:241], v[66:69]
	s_barrier
	s_setprio 0
	s_add_i32 s51, s51, s38
	v_lshl_add_u64 v[146:147], s[2:3], 0, v[134:135]
	s_mov_b32 m0, s51
	ds_read_b128 v[188:191], v151 offset:16384
	ds_read_b128 v[206:209], v151 offset:17408
	ds_read_b128 v[218:221], v151 offset:18432
	ds_read_b128 v[222:225], v151 offset:19456
	ds_read_b128 v[226:229], v151 offset:20480
	ds_read_b128 v[230:233], v151 offset:21504
	ds_read_b128 v[234:237], v151 offset:22528
	ds_read_b128 v[238:241], v151 offset:23552
	global_load_lds_dwordx4 v[146:147], off
	s_add_i32 m0, s51, 0x2000
	s_add_u32 s52, s2, 0x400000
	v_lshl_add_u64 v[176:177], s[2:3], 0, v[136:137]
	s_addc_u32 s53, s3, 0
	s_add_i32 s51, s54, s38
	global_load_lds_dwordx4 v[176:177], off
	v_lshl_add_u64 v[194:195], s[52:53], 0, v[134:135]
	s_mov_b32 m0, s51
	v_lshl_add_u64 v[210:211], s[30:31], 0, v[136:137]
	global_load_lds_dwordx4 v[194:195], off
	v_lshl_add_u64 v[194:195], s[52:53], 0, v[136:137]
	s_add_i32 m0, s51, 0x2000
	s_nop 0
	global_load_lds_dwordx4 v[194:195], off
	v_lshl_add_u64 v[194:195], s[30:31], 0, v[134:135]
	s_mov_b32 m0, s25
	s_nop 0
	global_load_lds_dwordx4 v[194:195], off
	s_mov_b32 m0, s27
	s_nop 0
	global_load_lds_dwordx4 v[210:211], off
	s_waitcnt vmcnt(8)
	s_waitcnt lgkmcnt(0)
	s_setprio 1
	s_barrier
; #define PG8_STAGE(bufoff, gbase, voff) do { _Pragma("unroll") for (int _i = 0; _i < 2; ++_i) \
;         __builtin_amdgcn_global_load_lds((const unsigned*)((const char*)(gbase) + (voff)[_i]), (PG8_LAS unsigned*)(lds + (bufoff) + ldsw + _i * 8192), 16, 0, 0); } while (0)
; #define PG8_LDA(dst, b, h) do { _Pragma("unroll") for (int m = 0; m < 4; ++m) _Pragma("unroll") for (int k = 0; k < 2; ++k) dst[m][k] = *(const PG8_LAS bf16x8*)(lds + PG8_SA(b, h) + aoff + m * 2048 + k * 1024); } while (0)
; #define PG8_LDB(dst, b, h) do { _Pragma("unroll") for (int n = 0; n < 2; ++n) _Pragma("unroll") for (int k = 0; k < 2; ++k) dst[n][k] = *(const PG8_LAS bf16x8*)(lds + PG8_SB(b, h) + boff + n * 2048 + k * 1024); } while (0)
; #define PG8_MMA(ai, bj, At, Bt) do { __builtin_amdgcn_s_setprio(1); _Pragma("unroll") for (int m = 0; m < 4; ++m) _Pragma("unroll") for (int n = 0; n < 2; ++n) _Pragma("unroll") for (int k = 0; k < 2; ++k) \
;         acc[ai][bj][m][n] = __builtin_amdgcn_mfma_f32_16x16x32_bf16(Bt[n][k], At[m][k], acc[ai][bj][m][n], 0, 0, 0); __builtin_amdgcn_s_setprio(0); } while (0)
; #define PG8_WAIT_V(n) asm volatile("s_waitcnt vmcnt(" #n ")" ::: "memory")
; #define PG8_WAIT_L(n) asm volatile("s_waitcnt lgkmcnt(" #n ")" ::: "memory")
; #define PG8_BAR __builtin_amdgcn_s_barrier()
; #define PG8_SCHED __builtin_amdgcn_sched_barrier(0)
; template <class Epi, class Sched, bool ALIGN_EPI, int LMASK = -1, int LMASKB = LMASK>
; __device__ __forceinline__ void gemm_phase(PG8_LAS unsigned char* lds, const Gemm g, const Sched& S, const Epi& E) {
;     ...
;             PG8_WAIT_V(8); PG8_WAIT_L(0); PG8_BAR; PG8_MMA(1, 0, At, B0); PG8_MMA(1, 1, At, B1); PG8_BAR; PG8_SCHED;
;             PG8_LDB(B0, 1, 0); PG8_LDB(B1, 1, 1); PG8_SCHED; PG8_LDA(At, 1, 0); PG8_STAGE(PG8_SA(0, 1), a2 + hstepA, voffA);
;             PG8_WAIT_V(8); PG8_WAIT_L(0); PG8_BAR; PG8_MMA(0, 0, At, B0); PG8_MMA(0, 1, At, B1); PG8_BAR; PG8_SCHED;
;             PG8_LDA(At, 1, 1); PG8_STAGE(PG8_SB(1, 0), b3, voffB); PG8_STAGE(PG8_SB(1, 1), b3 + hstepB, voffB); PG8_STAGE(PG8_SA(1, 0), a3, voffA);
	v_mfma_f32_16x16x32_bf16 v[62:65], v[130:133], v[188:191], v[62:65]
	v_mfma_f32_16x16x32_bf16 v[58:61], v[152:155], v[188:191], v[58:61]
	v_mfma_f32_16x16x32_bf16 v[46:49], v[130:133], v[218:221], v[46:49]
	v_mfma_f32_16x16x32_bf16 v[42:45], v[152:155], v[218:221], v[42:45]
	v_mfma_f32_16x16x32_bf16 v[30:33], v[130:133], v[226:229], v[30:33]
	v_mfma_f32_16x16x32_bf16 v[26:29], v[152:155], v[226:229], v[26:29]
	v_mfma_f32_16x16x32_bf16 v[14:17], v[130:133], v[234:237], v[14:17]
	v_mfma_f32_16x16x32_bf16 v[10:13], v[152:155], v[234:237], v[10:13]
	v_mfma_f32_16x16x32_bf16 v[62:65], v[142:145], v[206:209], v[62:65]
	v_mfma_f32_16x16x32_bf16 v[58:61], v[156:159], v[206:209], v[58:61]
	v_mfma_f32_16x16x32_bf16 v[46:49], v[142:145], v[222:225], v[46:49]
	v_mfma_f32_16x16x32_bf16 v[42:45], v[156:159], v[222:225], v[42:45]
	v_mfma_f32_16x16x32_bf16 v[30:33], v[142:145], v[230:233], v[30:33]
	v_mfma_f32_16x16x32_bf16 v[26:29], v[156:159], v[230:233], v[26:29]
	v_mfma_f32_16x16x32_bf16 v[14:17], v[142:145], v[238:241], v[14:17]
	v_mfma_f32_16x16x32_bf16 v[10:13], v[156:159], v[238:241], v[10:13]
	v_mfma_f32_16x16x32_bf16 v[54:57], v[160:163], v[188:191], v[54:57]
	v_mfma_f32_16x16x32_bf16 v[50:53], v[168:171], v[188:191], v[50:53]
	v_mfma_f32_16x16x32_bf16 v[38:41], v[160:163], v[218:221], v[38:41]
	v_mfma_f32_16x16x32_bf16 v[34:37], v[168:171], v[218:221], v[34:37]
	v_mfma_f32_16x16x32_bf16 v[22:25], v[160:163], v[226:229], v[22:25]
	v_mfma_f32_16x16x32_bf16 v[18:21], v[168:171], v[226:229], v[18:21]
	v_mfma_f32_16x16x32_bf16 v[6:9], v[160:163], v[234:237], v[6:9]
	v_mfma_f32_16x16x32_bf16 v[2:5], v[168:171], v[234:237], v[2:5]
	v_mfma_f32_16x16x32_bf16 v[54:57], v[164:167], v[206:209], v[54:57]
	v_mfma_f32_16x16x32_bf16 v[50:53], v[172:175], v[206:209], v[50:53]
	v_mfma_f32_16x16x32_bf16 v[38:41], v[164:167], v[222:225], v[38:41]
	v_mfma_f32_16x16x32_bf16 v[34:37], v[172:175], v[222:225], v[34:37]
	v_mfma_f32_16x16x32_bf16 v[22:25], v[164:167], v[230:233], v[22:25]
	v_mfma_f32_16x16x32_bf16 v[18:21], v[172:175], v[230:233], v[18:21]
	v_mfma_f32_16x16x32_bf16 v[6:9], v[164:167], v[238:241], v[6:9]
	v_mfma_f32_16x16x32_bf16 v[2:5], v[172:175], v[238:241], v[2:5]
	s_barrier
	s_setprio 0
	s_add_i32 s51, 0, 0x18000
	s_add_i32 s52, 0, 0x1c000
	v_add_u32_e32 v156, s51, v149
	v_add_u32_e32 v172, s52, v149
	ds_read_b128 v[130:133], v156
	ds_read_b128 v[142:145], v156 offset:1024
	ds_read_b128 v[152:155], v156 offset:2048
	ds_read_b128 v[156:159], v156 offset:3072
	ds_read_b128 v[160:163], v172
	ds_read_b128 v[164:167], v172 offset:1024
	ds_read_b128 v[168:171], v172 offset:2048
	ds_read_b128 v[172:175], v172 offset:3072
	s_add_u32 s30, s30, 0x400000
	s_addc_u32 s31, s31, 0
	s_mov_b32 m0, s39
	v_lshl_add_u64 v[212:213], s[30:31], 0, v[134:135]
	ds_read_b128 v[188:191], v151 offset:32768
	ds_read_b128 v[206:209], v151 offset:33792
	ds_read_b128 v[218:221], v151 offset:34816
	ds_read_b128 v[222:225], v151 offset:35840
	ds_read_b128 v[226:229], v151 offset:36864
	ds_read_b128 v[230:233], v151 offset:37888
	ds_read_b128 v[234:237], v151 offset:38912
	ds_read_b128 v[238:241], v151 offset:39936
	global_load_lds_dwordx4 v[212:213], off
	v_lshl_add_u64 v[212:213], s[30:31], 0, v[136:137]
	s_mov_b32 m0, s40
	s_nop 0
	global_load_lds_dwordx4 v[212:213], off
	s_waitcnt vmcnt(8)
	s_waitcnt lgkmcnt(0)
	s_setprio 1
	s_barrier
	v_mfma_f32_16x16x32_bf16 v[126:129], v[130:133], v[188:191], v[126:129]
	v_mfma_f32_16x16x32_bf16 v[122:125], v[152:155], v[188:191], v[122:125]
	v_mfma_f32_16x16x32_bf16 v[110:113], v[130:133], v[218:221], v[110:113]
	v_mfma_f32_16x16x32_bf16 v[106:109], v[152:155], v[218:221], v[106:109]
	v_mfma_f32_16x16x32_bf16 v[94:97], v[130:133], v[226:229], v[94:97]
	v_mfma_f32_16x16x32_bf16 v[90:93], v[152:155], v[226:229], v[90:93]
	v_mfma_f32_16x16x32_bf16 v[78:81], v[130:133], v[234:237], v[78:81]
	v_mfma_f32_16x16x32_bf16 v[74:77], v[152:155], v[234:237], v[74:77]
	v_mfma_f32_16x16x32_bf16 v[126:129], v[142:145], v[206:209], v[126:129]
	v_mfma_f32_16x16x32_bf16 v[122:125], v[156:159], v[206:209], v[122:125]
	v_mfma_f32_16x16x32_bf16 v[110:113], v[142:145], v[222:225], v[110:113]
	v_mfma_f32_16x16x32_bf16 v[106:109], v[156:159], v[222:225], v[106:109]
	v_mfma_f32_16x16x32_bf16 v[94:97], v[142:145], v[230:233], v[94:97]
	v_mfma_f32_16x16x32_bf16 v[90:93], v[156:159], v[230:233], v[90:93]
	v_mfma_f32_16x16x32_bf16 v[78:81], v[142:145], v[238:241], v[78:81]
	v_mfma_f32_16x16x32_bf16 v[74:77], v[156:159], v[238:241], v[74:77]
	v_mfma_f32_16x16x32_bf16 v[118:121], v[160:163], v[188:191], v[118:121]
	v_mfma_f32_16x16x32_bf16 v[114:117], v[168:171], v[188:191], v[114:117]
	v_mfma_f32_16x16x32_bf16 v[102:105], v[160:163], v[218:221], v[102:105]
	v_mfma_f32_16x16x32_bf16 v[98:101], v[168:171], v[218:221], v[98:101]
	v_mfma_f32_16x16x32_bf16 v[86:89], v[160:163], v[226:229], v[86:89]
	v_mfma_f32_16x16x32_bf16 v[82:85], v[168:171], v[226:229], v[82:85]
	v_mfma_f32_16x16x32_bf16 v[70:73], v[160:163], v[234:237], v[70:73]
	v_mfma_f32_16x16x32_bf16 v[66:69], v[168:171], v[234:237], v[66:69]
	v_mfma_f32_16x16x32_bf16 v[118:121], v[164:167], v[206:209], v[118:121]
	v_mfma_f32_16x16x32_bf16 v[114:117], v[172:175], v[206:209], v[114:117]
	v_mfma_f32_16x16x32_bf16 v[102:105], v[164:167], v[222:225], v[102:105]
	v_mfma_f32_16x16x32_bf16 v[98:101], v[172:175], v[222:225], v[98:101]
	v_mfma_f32_16x16x32_bf16 v[86:89], v[164:167], v[230:233], v[86:89]
	v_mfma_f32_16x16x32_bf16 v[82:85], v[172:175], v[230:233], v[82:85]
	v_mfma_f32_16x16x32_bf16 v[70:73], v[164:167], v[238:241], v[70:73]
	v_mfma_f32_16x16x32_bf16 v[66:69], v[172:175], v[238:241], v[66:69]
	s_barrier
; #define PG8_STAGE(bufoff, gbase, voff) do { _Pragma("unroll") for (int _i = 0; _i < 2; ++_i) \
;         __builtin_amdgcn_global_load_lds((const unsigned*)((const char*)(gbase) + (voff)[_i]), (PG8_LAS unsigned*)(lds + (bufoff) + ldsw + _i * 8192), 16, 0, 0); } while (0)
; #define PG8_LDA(dst, b, h) do { _Pragma("unroll") for (int m = 0; m < 4; ++m) _Pragma("unroll") for (int k = 0; k < 2; ++k) dst[m][k] = *(const PG8_LAS bf16x8*)(lds + PG8_SA(b, h) + aoff + m * 2048 + k * 1024); } while (0)
; #define PG8_MMA(ai, bj, At, Bt) do { __builtin_amdgcn_s_setprio(1); _Pragma("unroll") for (int m = 0; m < 4; ++m) _Pragma("unroll") for (int n = 0; n < 2; ++n) _Pragma("unroll") for (int k = 0; k < 2; ++k) \
;         acc[ai][bj][m][n] = __builtin_amdgcn_mfma_f32_16x16x32_bf16(Bt[n][k], At[m][k], acc[ai][bj][m][n], 0, 0, 0); __builtin_amdgcn_s_setprio(0); } while (0)
; #define PG8_WAIT_V(n) asm volatile("s_waitcnt vmcnt(" #n ")" ::: "memory")
; #define PG8_WAIT_L(n) asm volatile("s_waitcnt lgkmcnt(" #n ")" ::: "memory")
; #define PG8_BAR __builtin_amdgcn_s_barrier()
; #define PG8_SCHED __builtin_amdgcn_sched_barrier(0)
; template <class Epi, class Sched, bool ALIGN_EPI, int LMASK = -1, int LMASKB = LMASK>
; __device__ __forceinline__ void gemm_phase(PG8_LAS unsigned char* lds, const Gemm g, const Sched& S, const Epi& E) {
;     ...
;             PG8_LDA(At, 1, 1); PG8_STAGE(PG8_SB(1, 0), b3, voffB); PG8_STAGE(PG8_SB(1, 1), b3 + hstepB, voffB); PG8_STAGE(PG8_SA(1, 0), a3, voffA);
;             PG8_WAIT_V(8); PG8_WAIT_L(0); PG8_BAR; PG8_MMA(1, 0, At, B0); PG8_MMA(1, 1, At, B1); PG8_BAR; PG8_SCHED;
;         }
;         if constexpr (ALIGN_EPI) { if (wr == 0) PG8_BAR; }
	s_setprio 0
	s_add_i32 s30, s51, s38
	v_lshl_add_u64 v[146:147], v[146:147], 0, s[80:81]
	s_mov_b32 m0, s30
	ds_read_b128 v[188:191], v151 offset:49152
	ds_read_b128 v[206:209], v151 offset:50176
	ds_read_b128 v[218:221], v151 offset:51200
	ds_read_b128 v[222:225], v151 offset:52224
	ds_read_b128 v[226:229], v151 offset:53248
	ds_read_b128 v[230:233], v151 offset:54272
	ds_read_b128 v[234:237], v151 offset:55296
	ds_read_b128 v[238:241], v151 offset:56320
	global_load_lds_dwordx4 v[146:147], off
	s_add_i32 m0, s30, 0x2000
	s_add_u32 s2, s2, 0x400800
	v_lshl_add_u64 v[146:147], v[176:177], 0, s[80:81]
	s_addc_u32 s3, s3, 0
	s_add_i32 s30, s52, s38
	global_load_lds_dwordx4 v[146:147], off
	v_lshl_add_u64 v[146:147], s[2:3], 0, v[134:135]
	s_mov_b32 m0, s30
	s_nop 0
	global_load_lds_dwordx4 v[146:147], off
	v_lshl_add_u64 v[146:147], s[2:3], 0, v[136:137]
	s_add_i32 m0, s30, 0x2000
	s_nop 0
	global_load_lds_dwordx4 v[146:147], off
	v_lshl_add_u64 v[146:147], v[194:195], 0, s[80:81]
	s_mov_b32 m0, s41
	s_nop 0
	global_load_lds_dwordx4 v[146:147], off
	v_lshl_add_u64 v[146:147], v[210:211], 0, s[80:81]
	s_mov_b32 m0, s42
	s_nop 0
	global_load_lds_dwordx4 v[146:147], off
	s_waitcnt vmcnt(8)
	s_waitcnt lgkmcnt(0)
	s_setprio 1
	s_barrier
	v_mfma_f32_16x16x32_bf16 v[62:65], v[130:133], v[188:191], v[62:65]
	v_mfma_f32_16x16x32_bf16 v[58:61], v[152:155], v[188:191], v[58:61]
	v_mfma_f32_16x16x32_bf16 v[46:49], v[130:133], v[218:221], v[46:49]
	v_mfma_f32_16x16x32_bf16 v[42:45], v[152:155], v[218:221], v[42:45]
	v_mfma_f32_16x16x32_bf16 v[30:33], v[130:133], v[226:229], v[30:33]
	v_mfma_f32_16x16x32_bf16 v[26:29], v[152:155], v[226:229], v[26:29]
	v_mfma_f32_16x16x32_bf16 v[14:17], v[130:133], v[234:237], v[14:17]
	v_mfma_f32_16x16x32_bf16 v[10:13], v[152:155], v[234:237], v[10:13]
	v_mfma_f32_16x16x32_bf16 v[62:65], v[142:145], v[206:209], v[62:65]
	v_mfma_f32_16x16x32_bf16 v[58:61], v[156:159], v[206:209], v[58:61]
	v_mfma_f32_16x16x32_bf16 v[46:49], v[142:145], v[222:225], v[46:49]
	v_mfma_f32_16x16x32_bf16 v[42:45], v[156:159], v[222:225], v[42:45]
	v_mfma_f32_16x16x32_bf16 v[30:33], v[142:145], v[230:233], v[30:33]
	v_mfma_f32_16x16x32_bf16 v[26:29], v[156:159], v[230:233], v[26:29]
	v_mfma_f32_16x16x32_bf16 v[14:17], v[142:145], v[238:241], v[14:17]
	v_mfma_f32_16x16x32_bf16 v[10:13], v[156:159], v[238:241], v[10:13]
	v_mfma_f32_16x16x32_bf16 v[54:57], v[160:163], v[188:191], v[54:57]
	v_mfma_f32_16x16x32_bf16 v[50:53], v[168:171], v[188:191], v[50:53]
	v_mfma_f32_16x16x32_bf16 v[38:41], v[160:163], v[218:221], v[38:41]
	v_mfma_f32_16x16x32_bf16 v[34:37], v[168:171], v[218:221], v[34:37]
	v_mfma_f32_16x16x32_bf16 v[22:25], v[160:163], v[226:229], v[22:25]
	v_mfma_f32_16x16x32_bf16 v[18:21], v[168:171], v[226:229], v[18:21]
	v_mfma_f32_16x16x32_bf16 v[6:9], v[160:163], v[234:237], v[6:9]
	v_mfma_f32_16x16x32_bf16 v[2:5], v[168:171], v[234:237], v[2:5]
	v_mfma_f32_16x16x32_bf16 v[54:57], v[164:167], v[206:209], v[54:57]
	v_mfma_f32_16x16x32_bf16 v[50:53], v[172:175], v[206:209], v[50:53]
	v_mfma_f32_16x16x32_bf16 v[38:41], v[164:167], v[222:225], v[38:41]
	v_mfma_f32_16x16x32_bf16 v[34:37], v[172:175], v[222:225], v[34:37]
	v_mfma_f32_16x16x32_bf16 v[22:25], v[164:167], v[230:233], v[22:25]
	v_mfma_f32_16x16x32_bf16 v[18:21], v[172:175], v[230:233], v[18:21]
	v_mfma_f32_16x16x32_bf16 v[6:9], v[164:167], v[238:241], v[6:9]
	v_mfma_f32_16x16x32_bf16 v[2:5], v[172:175], v[238:241], v[2:5]
	s_barrier
	s_setprio 0
	s_add_i32 s50, s50, 2
	s_add_u32 s28, s28, 0x1000
	s_addc_u32 s29, s29, 0
	s_add_u32 s48, s48, 0x1000
	s_addc_u32 s49, s49, 0
	s_cmpk_gt_u32 s50, 0xfd
	s_cbranch_scc0 .LBB0_761
	s_and_b64 vcc, exec, s[14:15]
	s_cbranch_vccz .LBB0_764
	s_barrier
